# v093 + attention: DMA pieces without s_nop, step-1 pad shortened, two moves folded into early exps, scalar band flag; GEMM K-loops: two LDS base addresses hoisted out of the loop
# speedup vs baseline: 1.0050x; 1.0050x over previous
; #define PG8_STAGE(bufoff, gbase, voff) do { _Pragma("unroll") for (int _i = 0; _i < 2; ++_i) \
;         __builtin_amdgcn_global_load_lds((const unsigned*)((const char*)(gbase) + (voff)[_i]), (PG8_LAS unsigned*)(lds + (bufoff) + ldsw + _i * 8192), 16, 0, 0); } while (0)
; #define PG8_LDA(dst, b, h) do { _Pragma("unroll") for (int m = 0; m < 4; ++m) _Pragma("unroll") for (int k = 0; k < 2; ++k) dst[m][k] = *(const PG8_LAS bf16x8*)(lds + PG8_SA(b, h) + aoff + m * 2048 + k * 1024); } while (0)
; #define PG8_LDB(dst, b, h) do { _Pragma("unroll") for (int n = 0; n < 2; ++n) _Pragma("unroll") for (int k = 0; k < 2; ++k) dst[n][k] = *(const PG8_LAS bf16x8*)(lds + PG8_SB(b, h) + boff + n * 2048 + k * 1024); } while (0)
; #define PG8_SCHED __builtin_amdgcn_sched_barrier(0)
; template <class Epi, class Sched, bool ALIGN_EPI = false, bool SP2 = false>
; __device__ __forceinline__ void gemm_phase(PG8_LAS unsigned char* lds, const Gemm g, const Sched& S, const Epi& E) {
;     ...
;         const char* nA = has_next ? (const char*)g.A + (size_t)nxt.pm * tstep + (size_t)nxt.pn * g.a_pn_off : cA; const char* nB = has_next ? (const char*)g.Bt + (size_t)nxt.pn * tstep : cB;
;         for (int t = 0; t < nt; t += 2) {
;             const bool last = (t == nt - 2);
;             const char* a1 = cA + (size_t)(t + 1) * kstep;
;             const char* a2 = last ? nA : cA + (size_t)(t + 2) * kstep; const char* b2 = last ? nB : cB + (size_t)(t + 2) * kstep;
;             const char* a3 = a2 + kstep; const char* b3 = b2 + kstep;
;             if (last && has_next) S.a_ready(nxt);
;             if constexpr (SP2) {
;             PG8_LDB(B0, 0, 0); PG8_LDB(B1, 0, 1); PG8_SCHED; PG8_LDA(At, 0, 0); PG8_STAGE(PG8_SA(1, 1), a1 + hstep, voffA);
;     ...
;         for (int a = 0; a < 2; ++a)
; #pragma unroll
;             for (int b = 0; b < 2; ++b)
; #pragma unroll
;                 for (int m = 0; m < 4; ++m)
; #pragma unroll
;                     for (int n = 0; n < 2; ++n) acc[a][b][m][n] = (f32x4){0.f, 0.f, 0.f, 0.f};
.LBB0_118:
	s_ashr_i32 s19, s18, 31
	s_lshl_b64 s[20:21], s[18:19], 19
	s_add_u32 s20, s46, s20
	s_addc_u32 s21, s47, s21
	s_and_b64 s[22:23], s[2:3], exec
	s_cselect_b32 s5, s21, s25
	s_cselect_b32 s7, s20, s24
	s_ashr_i32 s17, s16, 31
	s_lshl_b64 s[22:23], s[16:17], 19
	s_add_u32 s22, s74, s22
	s_addc_u32 s23, s75, s23
	s_and_b64 s[28:29], s[2:3], exec
	s_cselect_b32 s17, s23, s27
	s_cselect_b32 s19, s22, s26
	s_add_u32 s24, s24, 0x40080
	s_addc_u32 s25, s25, 0
	s_add_u32 s36, s26, 0x100
	v_mov_b32_e32 v0, 0
	s_addc_u32 s37, s27, 0
	s_mov_b32 s50, -2
	v_mov_b32_e32 v1, v0
	v_mov_b32_e32 v2, v0
	v_mov_b32_e32 v3, v0
	v_mov_b32_e32 v4, v0
	v_mov_b32_e32 v5, v0
	v_mov_b32_e32 v6, v0
	v_mov_b32_e32 v7, v0
	v_mov_b32_e32 v16, v0
	v_mov_b32_e32 v17, v0
	v_mov_b32_e32 v18, v0
	v_mov_b32_e32 v19, v0
	v_mov_b32_e32 v20, v0
	v_mov_b32_e32 v21, v0
	v_mov_b32_e32 v22, v0
	v_mov_b32_e32 v23, v0
	v_mov_b32_e32 v32, v0
	v_mov_b32_e32 v33, v0
	v_mov_b32_e32 v34, v0
	v_mov_b32_e32 v35, v0
	v_mov_b32_e32 v36, v0
	v_mov_b32_e32 v37, v0
	v_mov_b32_e32 v38, v0
	v_mov_b32_e32 v39, v0
	v_mov_b32_e32 v48, v0
	v_mov_b32_e32 v49, v0
	v_mov_b32_e32 v50, v0
	v_mov_b32_e32 v51, v0
	v_mov_b32_e32 v52, v0
	v_mov_b32_e32 v53, v0
	v_mov_b32_e32 v54, v0
	v_mov_b32_e32 v55, v0
	v_mov_b32_e32 v8, v0
	v_mov_b32_e32 v9, v0
	v_mov_b32_e32 v10, v0
	v_mov_b32_e32 v11, v0
	v_mov_b32_e32 v12, v0
	v_mov_b32_e32 v13, v0
	v_mov_b32_e32 v14, v0
	v_mov_b32_e32 v15, v0
	v_mov_b32_e32 v24, v0
	v_mov_b32_e32 v25, v0
	v_mov_b32_e32 v26, v0
	v_mov_b32_e32 v27, v0
	v_mov_b32_e32 v28, v0
	v_mov_b32_e32 v29, v0
	v_mov_b32_e32 v30, v0
	v_mov_b32_e32 v31, v0
	v_mov_b32_e32 v40, v0
	v_mov_b32_e32 v41, v0
	v_mov_b32_e32 v42, v0
	v_mov_b32_e32 v43, v0
	v_mov_b32_e32 v44, v0
	v_mov_b32_e32 v45, v0
	v_mov_b32_e32 v46, v0
	v_mov_b32_e32 v47, v0
	v_mov_b32_e32 v64, v0
	v_mov_b32_e32 v65, v0
	v_mov_b32_e32 v66, v0
	v_mov_b32_e32 v67, v0
	v_mov_b32_e32 v68, v0
	v_mov_b32_e32 v69, v0
	v_mov_b32_e32 v70, v0
	v_mov_b32_e32 v71, v0
	v_mov_b32_e32 v72, v0
	v_mov_b32_e32 v73, v0
	v_mov_b32_e32 v74, v0
	v_mov_b32_e32 v75, v0
	v_mov_b32_e32 v76, v0
	v_mov_b32_e32 v77, v0
	v_mov_b32_e32 v78, v0
	v_mov_b32_e32 v79, v0
	v_mov_b32_e32 v88, v0
	v_mov_b32_e32 v89, v0
	v_mov_b32_e32 v90, v0
	v_mov_b32_e32 v91, v0
	v_mov_b32_e32 v92, v0
	v_mov_b32_e32 v93, v0
	v_mov_b32_e32 v94, v0
	v_mov_b32_e32 v95, v0
	v_mov_b32_e32 v104, v0
	v_mov_b32_e32 v105, v0
	v_mov_b32_e32 v106, v0
	v_mov_b32_e32 v107, v0
	v_mov_b32_e32 v108, v0
	v_mov_b32_e32 v109, v0
	v_mov_b32_e32 v110, v0
	v_mov_b32_e32 v111, v0
	v_mov_b32_e32 v120, v0
	v_mov_b32_e32 v121, v0
	v_mov_b32_e32 v122, v0
	v_mov_b32_e32 v123, v0
	v_mov_b32_e32 v124, v0
	v_mov_b32_e32 v125, v0
	v_mov_b32_e32 v126, v0
	v_mov_b32_e32 v127, v0
	v_mov_b32_e32 v80, v0
	v_mov_b32_e32 v81, v0
	v_mov_b32_e32 v82, v0
	v_mov_b32_e32 v83, v0
	v_mov_b32_e32 v84, v0
	v_mov_b32_e32 v85, v0
	v_mov_b32_e32 v86, v0
	v_mov_b32_e32 v87, v0
	v_mov_b32_e32 v96, v0
	v_mov_b32_e32 v97, v0
	v_mov_b32_e32 v98, v0
	v_mov_b32_e32 v99, v0
	v_mov_b32_e32 v100, v0
	v_mov_b32_e32 v101, v0
	v_mov_b32_e32 v102, v0
	v_mov_b32_e32 v103, v0
	v_mov_b32_e32 v112, v0
	v_mov_b32_e32 v113, v0
	v_mov_b32_e32 v114, v0
	v_mov_b32_e32 v115, v0
	v_mov_b32_e32 v116, v0
	v_mov_b32_e32 v117, v0
	v_mov_b32_e32 v118, v0
	v_mov_b32_e32 v119, v0
	v_mov_b32_e32 v128, v0
	v_mov_b32_e32 v129, v0
	v_mov_b32_e32 v130, v0
	v_mov_b32_e32 v131, v0
	v_mov_b32_e32 v132, v0
	v_mov_b32_e32 v133, v0
	v_mov_b32_e32 v134, v0
	v_mov_b32_e32 v135, v0
	v_add_u32_e32 v240, 0x18000, v165
	v_add_u32_e32 v241, 0x1c000, v165
.LBB0_119:
	ds_read_b128 v[56:59], v167
	ds_read_b128 v[60:63], v167 offset:1024
	ds_read_b128 v[136:139], v167 offset:2048
	ds_read_b128 v[158:161], v167 offset:3072
	ds_read_b128 v[170:173], v168
	ds_read_b128 v[174:177], v168 offset:1024
	ds_read_b128 v[178:181], v168 offset:2048
	ds_read_b128 v[182:185], v168 offset:3072
	s_add_u32 s26, s24, 0xfffc0080
	s_addc_u32 s27, s25, -1
	s_cmp_eq_u32 s50, 12
	s_cselect_b32 s29, s5, s27
	s_cselect_b32 s28, s7, s26
	s_cselect_b32 s27, s17, s37
	s_cselect_b32 s26, s19, s36
	s_add_u32 vcc_lo, s26, 0x80
	s_addc_u32 vcc_hi, s27, 0
	s_add_u32 s100, s28, 0x80
	s_addc_u32 s101, s29, 0
	s_add_i32 m0, s31, 0xc000
	ds_read_b128 v[186:189], v169
	ds_read_b128 v[194:197], v169 offset:1024
	ds_read_b128 v[198:201], v169 offset:2048
	ds_read_b128 v[202:205], v169 offset:3072
	ds_read_b128 v[206:209], v169 offset:4096
	ds_read_b128 v[210:213], v169 offset:5120
	ds_read_b128 v[214:217], v169 offset:6144
	global_load_lds_dwordx4 v150, s[24:25]
	s_add_i32 m0, s31, 0xe000
	ds_read_b128 v[218:221], v169 offset:7168
	global_load_lds_dwordx4 v152, s[24:25]
	s_waitcnt vmcnt(8)
	s_waitcnt lgkmcnt(0)
	s_barrier
; #define PG8_STAGE(bufoff, gbase, voff) do { _Pragma("unroll") for (int _i = 0; _i < 2; ++_i) \
;         __builtin_amdgcn_global_load_lds((const unsigned*)((const char*)(gbase) + (voff)[_i]), (PG8_LAS unsigned*)(lds + (bufoff) + ldsw + _i * 8192), 16, 0, 0); } while (0)
; #define PG8_LDA(dst, b, h) do { _Pragma("unroll") for (int m = 0; m < 4; ++m) _Pragma("unroll") for (int k = 0; k < 2; ++k) dst[m][k] = *(const PG8_LAS bf16x8*)(lds + PG8_SA(b, h) + aoff + m * 2048 + k * 1024); } while (0)
; #define PG8_MMA(ai, bj, At, Bt) do { __builtin_amdgcn_s_setprio(1); _Pragma("unroll") for (int m = 0; m < 4; ++m) _Pragma("unroll") for (int n = 0; n < 2; ++n) _Pragma("unroll") for (int k = 0; k < 2; ++k) \
;         acc[ai][bj][m][n] = __builtin_amdgcn_mfma_f32_16x16x32_bf16(Bt[n][k], At[m][k], acc[ai][bj][m][n], 0, 0, 0); __builtin_amdgcn_s_setprio(0); } while (0)
; #define PG8_WAIT_V(n) asm volatile("s_waitcnt vmcnt(" #n ")" ::: "memory")
; #define PG8_WAIT_L(n) asm volatile("s_waitcnt lgkmcnt(" #n ")" ::: "memory")
; #define PG8_BAR __builtin_amdgcn_s_barrier()
; #define PG8_SCHED __builtin_amdgcn_sched_barrier(0)
; template <class Epi, class Sched, bool ALIGN_EPI = false, bool SP2 = false>
; __device__ __forceinline__ void gemm_phase(PG8_LAS unsigned char* lds, const Gemm g, const Sched& S, const Epi& E) {
;     ...
;             PG8_WAIT_V(8); PG8_WAIT_L(0); PG8_BAR; PG8_MMA(0, 0, At, B0); PG8_MMA(0, 1, At, B1); PG8_BAR; PG8_SCHED;
;             PG8_LDA(At, 0, 1); PG8_STAGE(PG8_SB(0, 0), b2, voffB); PG8_STAGE(PG8_SB(0, 1), b2 + hstep, voffB); PG8_STAGE(PG8_SA(0, 0), a2, voffA);
;             PG8_WAIT_V(8); PG8_WAIT_L(0); PG8_BAR; PG8_MMA(1, 0, At, B0); PG8_MMA(1, 1, At, B1); PG8_BAR; PG8_SCHED;
	s_setprio 1
	s_waitcnt lgkmcnt(0)
	v_mfma_f32_16x16x32_bf16 v[132:135], v[56:59], v[186:189], v[132:135]
	v_mfma_f32_16x16x32_bf16 v[128:131], v[136:139], v[186:189], v[128:131]
	v_mfma_f32_16x16x32_bf16 v[116:119], v[56:59], v[198:201], v[116:119]
	v_mfma_f32_16x16x32_bf16 v[112:115], v[136:139], v[198:201], v[112:115]
	v_mfma_f32_16x16x32_bf16 v[100:103], v[56:59], v[206:209], v[100:103]
	v_mfma_f32_16x16x32_bf16 v[96:99], v[136:139], v[206:209], v[96:99]
	v_mfma_f32_16x16x32_bf16 v[84:87], v[56:59], v[214:217], v[84:87]
	v_mfma_f32_16x16x32_bf16 v[80:83], v[136:139], v[214:217], v[80:83]
	v_mfma_f32_16x16x32_bf16 v[132:135], v[60:63], v[194:197], v[132:135]
	v_mfma_f32_16x16x32_bf16 v[128:131], v[158:161], v[194:197], v[128:131]
	v_mfma_f32_16x16x32_bf16 v[116:119], v[60:63], v[202:205], v[116:119]
	v_mfma_f32_16x16x32_bf16 v[112:115], v[158:161], v[202:205], v[112:115]
	v_mfma_f32_16x16x32_bf16 v[100:103], v[60:63], v[210:213], v[100:103]
	v_mfma_f32_16x16x32_bf16 v[96:99], v[158:161], v[210:213], v[96:99]
	v_mfma_f32_16x16x32_bf16 v[84:87], v[60:63], v[218:221], v[84:87]
	v_mfma_f32_16x16x32_bf16 v[80:83], v[158:161], v[218:221], v[80:83]
	s_setprio 0
	s_setprio 1
	v_mfma_f32_16x16x32_bf16 v[124:127], v[170:173], v[186:189], v[124:127]
	v_mfma_f32_16x16x32_bf16 v[120:123], v[178:181], v[186:189], v[120:123]
	v_mfma_f32_16x16x32_bf16 v[108:111], v[170:173], v[198:201], v[108:111]
	v_mfma_f32_16x16x32_bf16 v[104:107], v[178:181], v[198:201], v[104:107]
	v_mfma_f32_16x16x32_bf16 v[92:95], v[170:173], v[206:209], v[92:95]
	v_mfma_f32_16x16x32_bf16 v[88:91], v[178:181], v[206:209], v[88:91]
	v_mfma_f32_16x16x32_bf16 v[76:79], v[170:173], v[214:217], v[76:79]
	v_mfma_f32_16x16x32_bf16 v[72:75], v[178:181], v[214:217], v[72:75]
	v_mfma_f32_16x16x32_bf16 v[124:127], v[174:177], v[194:197], v[124:127]
	v_mfma_f32_16x16x32_bf16 v[120:123], v[182:185], v[194:197], v[120:123]
	v_mfma_f32_16x16x32_bf16 v[108:111], v[174:177], v[202:205], v[108:111]
	v_mfma_f32_16x16x32_bf16 v[104:107], v[182:185], v[202:205], v[104:107]
	v_mfma_f32_16x16x32_bf16 v[92:95], v[174:177], v[210:213], v[92:95]
	v_mfma_f32_16x16x32_bf16 v[88:91], v[182:185], v[210:213], v[88:91]
	v_mfma_f32_16x16x32_bf16 v[76:79], v[174:177], v[218:221], v[76:79]
	v_mfma_f32_16x16x32_bf16 v[72:75], v[182:185], v[218:221], v[72:75]
	s_setprio 0
	s_barrier
	s_add_i32 s51, s88, s58
	s_mov_b32 m0, s51
	ds_read_b128 v[186:189], v169 offset:16384
	ds_read_b128 v[194:197], v169 offset:17408
	ds_read_b128 v[198:201], v169 offset:18432
	ds_read_b128 v[202:205], v169 offset:19456
	global_load_lds_dwordx4 v142, s[26:27]
	s_add_i32 m0, s51, 0x2000
	s_add_u32 s76, s26, 0x40000
	s_addc_u32 s77, s27, 0
	s_add_i32 s51, s89, s58
	global_load_lds_dwordx4 v146, s[26:27]
	s_mov_b32 m0, s51
	ds_read_b128 v[218:221], v169 offset:23552
	global_load_lds_dwordx4 v142, s[76:77]
	s_add_i32 m0, s51, 0x2000
	ds_read_b128 v[214:217], v169 offset:22528
	global_load_lds_dwordx4 v146, s[76:77]
	s_mov_b32 m0, s31
	ds_read_b128 v[210:213], v169 offset:21504
	global_load_lds_dwordx4 v140, s[28:29]
	s_mov_b32 m0, s0
	ds_read_b128 v[206:209], v169 offset:20480
	global_load_lds_dwordx4 v144, s[28:29]
	s_waitcnt vmcnt(8)
	s_waitcnt lgkmcnt(0)
	s_barrier
	s_setprio 1
	s_waitcnt lgkmcnt(0)
	v_mfma_f32_16x16x32_bf16 v[68:71], v[56:59], v[186:189], v[68:71]
	v_mfma_f32_16x16x32_bf16 v[64:67], v[136:139], v[186:189], v[64:67]
	v_mfma_f32_16x16x32_bf16 v[44:47], v[56:59], v[198:201], v[44:47]
	v_mfma_f32_16x16x32_bf16 v[40:43], v[136:139], v[198:201], v[40:43]
	v_mfma_f32_16x16x32_bf16 v[28:31], v[56:59], v[206:209], v[28:31]
	v_mfma_f32_16x16x32_bf16 v[24:27], v[136:139], v[206:209], v[24:27]
	v_mfma_f32_16x16x32_bf16 v[12:15], v[56:59], v[214:217], v[12:15]
	v_mfma_f32_16x16x32_bf16 v[8:11], v[136:139], v[214:217], v[8:11]
	v_mfma_f32_16x16x32_bf16 v[68:71], v[60:63], v[194:197], v[68:71]
	v_mfma_f32_16x16x32_bf16 v[64:67], v[158:161], v[194:197], v[64:67]
	v_mfma_f32_16x16x32_bf16 v[44:47], v[60:63], v[202:205], v[44:47]
	v_mfma_f32_16x16x32_bf16 v[40:43], v[158:161], v[202:205], v[40:43]
	v_mfma_f32_16x16x32_bf16 v[28:31], v[60:63], v[210:213], v[28:31]
	v_mfma_f32_16x16x32_bf16 v[24:27], v[158:161], v[210:213], v[24:27]
	v_mfma_f32_16x16x32_bf16 v[12:15], v[60:63], v[218:221], v[12:15]
	v_mfma_f32_16x16x32_bf16 v[8:11], v[158:161], v[218:221], v[8:11]
	s_setprio 0
	s_setprio 1
	v_mfma_f32_16x16x32_bf16 v[52:55], v[170:173], v[186:189], v[52:55]
	v_mfma_f32_16x16x32_bf16 v[48:51], v[178:181], v[186:189], v[48:51]
	v_mfma_f32_16x16x32_bf16 v[36:39], v[170:173], v[198:201], v[36:39]
	v_mfma_f32_16x16x32_bf16 v[32:35], v[178:181], v[198:201], v[32:35]
	v_mfma_f32_16x16x32_bf16 v[20:23], v[170:173], v[206:209], v[20:23]
	v_mfma_f32_16x16x32_bf16 v[16:19], v[178:181], v[206:209], v[16:19]
	v_mfma_f32_16x16x32_bf16 v[4:7], v[170:173], v[214:217], v[4:7]
	v_mfma_f32_16x16x32_bf16 v[0:3], v[178:181], v[214:217], v[0:3]
	v_mfma_f32_16x16x32_bf16 v[52:55], v[174:177], v[194:197], v[52:55]
	v_mfma_f32_16x16x32_bf16 v[48:51], v[182:185], v[194:197], v[48:51]
	v_mfma_f32_16x16x32_bf16 v[36:39], v[174:177], v[202:205], v[36:39]
	v_mfma_f32_16x16x32_bf16 v[32:35], v[182:185], v[202:205], v[32:35]
	v_mfma_f32_16x16x32_bf16 v[20:23], v[174:177], v[210:213], v[20:23]
	v_mfma_f32_16x16x32_bf16 v[16:19], v[182:185], v[210:213], v[16:19]
	v_mfma_f32_16x16x32_bf16 v[4:7], v[174:177], v[218:221], v[4:7]
	v_mfma_f32_16x16x32_bf16 v[0:3], v[182:185], v[218:221], v[0:3]
	s_setprio 0
	s_barrier
; #define PG8_STAGE(bufoff, gbase, voff) do { _Pragma("unroll") for (int _i = 0; _i < 2; ++_i) \
;         __builtin_amdgcn_global_load_lds((const unsigned*)((const char*)(gbase) + (voff)[_i]), (PG8_LAS unsigned*)(lds + (bufoff) + ldsw + _i * 8192), 16, 0, 0); } while (0)
; #define PG8_LDA(dst, b, h) do { _Pragma("unroll") for (int m = 0; m < 4; ++m) _Pragma("unroll") for (int k = 0; k < 2; ++k) dst[m][k] = *(const PG8_LAS bf16x8*)(lds + PG8_SA(b, h) + aoff + m * 2048 + k * 1024); } while (0)
; #define PG8_LDB(dst, b, h) do { _Pragma("unroll") for (int n = 0; n < 2; ++n) _Pragma("unroll") for (int k = 0; k < 2; ++k) dst[n][k] = *(const PG8_LAS bf16x8*)(lds + PG8_SB(b, h) + boff + n * 2048 + k * 1024); } while (0)
; #define PG8_MMA(ai, bj, At, Bt) do { __builtin_amdgcn_s_setprio(1); _Pragma("unroll") for (int m = 0; m < 4; ++m) _Pragma("unroll") for (int n = 0; n < 2; ++n) _Pragma("unroll") for (int k = 0; k < 2; ++k) \
;         acc[ai][bj][m][n] = __builtin_amdgcn_mfma_f32_16x16x32_bf16(Bt[n][k], At[m][k], acc[ai][bj][m][n], 0, 0, 0); __builtin_amdgcn_s_setprio(0); } while (0)
; #define PG8_WAIT_V(n) asm volatile("s_waitcnt vmcnt(" #n ")" ::: "memory")
; #define PG8_WAIT_L(n) asm volatile("s_waitcnt lgkmcnt(" #n ")" ::: "memory")
; #define PG8_BAR __builtin_amdgcn_s_barrier()
; #define PG8_SCHED __builtin_amdgcn_sched_barrier(0)
; template <class Epi, class Sched, bool ALIGN_EPI = false, bool SP2 = false>
; __device__ __forceinline__ void gemm_phase(PG8_LAS unsigned char* lds, const Gemm g, const Sched& S, const Epi& E) {
;     ...
;             PG8_LDB(B0, 1, 0); PG8_LDB(B1, 1, 1); PG8_SCHED; PG8_LDA(At, 1, 0); PG8_STAGE(PG8_SA(0, 1), a2 + hstep, voffA);
;             PG8_WAIT_V(8); PG8_WAIT_L(0); PG8_BAR; PG8_MMA(0, 0, At, B0); PG8_MMA(0, 1, At, B1); PG8_BAR; PG8_SCHED;
;             PG8_LDA(At, 1, 1); PG8_STAGE(PG8_SB(1, 0), b3, voffB); PG8_STAGE(PG8_SB(1, 1), b3 + hstep, voffB); PG8_STAGE(PG8_SA(1, 0), a3, voffA);
;             PG8_WAIT_V(8); PG8_WAIT_L(0); PG8_BAR; PG8_MMA(1, 0, At, B0); PG8_MMA(1, 1, At, B1); PG8_BAR; PG8_SCHED;
	s_add_i32 s51, 0, 0x18000
	s_add_i32 s76, 0, 0x1c000
	ds_read_b128 v[56:59], v240
	ds_read_b128 v[60:63], v240 offset:1024
	ds_read_b128 v[136:139], v240 offset:2048
	ds_read_b128 v[158:161], v240 offset:3072
	ds_read_b128 v[170:173], v241
	ds_read_b128 v[174:177], v241 offset:1024
	ds_read_b128 v[178:181], v241 offset:2048
	ds_read_b128 v[182:185], v241 offset:3072
	s_add_u32 s28, s28, 0x40000
	s_addc_u32 s29, s29, 0
	s_mov_b32 m0, s1
	ds_read_b128 v[186:189], v169 offset:32768
	ds_read_b128 v[194:197], v169 offset:33792
	ds_read_b128 v[198:201], v169 offset:34816
	ds_read_b128 v[202:205], v169 offset:35840
	ds_read_b128 v[206:209], v169 offset:36864
	ds_read_b128 v[210:213], v169 offset:37888
	ds_read_b128 v[214:217], v169 offset:38912
	global_load_lds_dwordx4 v140, s[28:29]
	s_mov_b32 m0, s38
	ds_read_b128 v[218:221], v169 offset:39936
	global_load_lds_dwordx4 v144, s[28:29]
	s_waitcnt vmcnt(8)
	s_waitcnt lgkmcnt(0)
	s_barrier
	s_setprio 1
	s_waitcnt lgkmcnt(0)
	v_mfma_f32_16x16x32_bf16 v[132:135], v[56:59], v[186:189], v[132:135]
	v_mfma_f32_16x16x32_bf16 v[128:131], v[136:139], v[186:189], v[128:131]
	v_mfma_f32_16x16x32_bf16 v[116:119], v[56:59], v[198:201], v[116:119]
	v_mfma_f32_16x16x32_bf16 v[112:115], v[136:139], v[198:201], v[112:115]
	v_mfma_f32_16x16x32_bf16 v[100:103], v[56:59], v[206:209], v[100:103]
	v_mfma_f32_16x16x32_bf16 v[96:99], v[136:139], v[206:209], v[96:99]
	v_mfma_f32_16x16x32_bf16 v[84:87], v[56:59], v[214:217], v[84:87]
	v_mfma_f32_16x16x32_bf16 v[80:83], v[136:139], v[214:217], v[80:83]
	v_mfma_f32_16x16x32_bf16 v[132:135], v[60:63], v[194:197], v[132:135]
	v_mfma_f32_16x16x32_bf16 v[128:131], v[158:161], v[194:197], v[128:131]
	v_mfma_f32_16x16x32_bf16 v[116:119], v[60:63], v[202:205], v[116:119]
	v_mfma_f32_16x16x32_bf16 v[112:115], v[158:161], v[202:205], v[112:115]
	v_mfma_f32_16x16x32_bf16 v[100:103], v[60:63], v[210:213], v[100:103]
	v_mfma_f32_16x16x32_bf16 v[96:99], v[158:161], v[210:213], v[96:99]
	v_mfma_f32_16x16x32_bf16 v[84:87], v[60:63], v[218:221], v[84:87]
	v_mfma_f32_16x16x32_bf16 v[80:83], v[158:161], v[218:221], v[80:83]
	s_setprio 0
	s_setprio 1
	v_mfma_f32_16x16x32_bf16 v[124:127], v[170:173], v[186:189], v[124:127]
	v_mfma_f32_16x16x32_bf16 v[120:123], v[178:181], v[186:189], v[120:123]
	v_mfma_f32_16x16x32_bf16 v[108:111], v[170:173], v[198:201], v[108:111]
	v_mfma_f32_16x16x32_bf16 v[104:107], v[178:181], v[198:201], v[104:107]
	v_mfma_f32_16x16x32_bf16 v[92:95], v[170:173], v[206:209], v[92:95]
	v_mfma_f32_16x16x32_bf16 v[88:91], v[178:181], v[206:209], v[88:91]
	v_mfma_f32_16x16x32_bf16 v[76:79], v[170:173], v[214:217], v[76:79]
	v_mfma_f32_16x16x32_bf16 v[72:75], v[178:181], v[214:217], v[72:75]
	v_mfma_f32_16x16x32_bf16 v[124:127], v[174:177], v[194:197], v[124:127]
	v_mfma_f32_16x16x32_bf16 v[120:123], v[182:185], v[194:197], v[120:123]
	v_mfma_f32_16x16x32_bf16 v[108:111], v[174:177], v[202:205], v[108:111]
	v_mfma_f32_16x16x32_bf16 v[104:107], v[182:185], v[202:205], v[104:107]
	v_mfma_f32_16x16x32_bf16 v[92:95], v[174:177], v[210:213], v[92:95]
	v_mfma_f32_16x16x32_bf16 v[88:91], v[182:185], v[210:213], v[88:91]
	v_mfma_f32_16x16x32_bf16 v[76:79], v[174:177], v[218:221], v[76:79]
	v_mfma_f32_16x16x32_bf16 v[72:75], v[182:185], v[218:221], v[72:75]
	s_setprio 0
	s_barrier
	s_add_i32 s28, s51, s58
	s_mov_b32 m0, s28
	ds_read_b128 v[186:189], v169 offset:49152
	ds_read_b128 v[194:197], v169 offset:50176
	ds_read_b128 v[198:201], v169 offset:51200
	ds_read_b128 v[202:205], v169 offset:52224
	global_load_lds_dwordx4 v142, vcc
	s_add_i32 m0, s28, 0x2000
	s_add_u32 s26, s26, 0x40080
	s_addc_u32 s27, s27, 0
	s_add_i32 s28, s76, s58
	global_load_lds_dwordx4 v146, vcc
	s_mov_b32 m0, s28
	ds_read_b128 v[218:221], v169 offset:56320
	global_load_lds_dwordx4 v142, s[26:27]
	s_add_i32 m0, s28, 0x2000
	ds_read_b128 v[214:217], v169 offset:55296
	global_load_lds_dwordx4 v146, s[26:27]
	s_mov_b32 m0, s42
	ds_read_b128 v[210:213], v169 offset:54272
	global_load_lds_dwordx4 v140, s[100:101]
	s_mov_b32 m0, s59
	ds_read_b128 v[206:209], v169 offset:53248
	global_load_lds_dwordx4 v144, s[100:101]
	s_waitcnt vmcnt(8)
	s_waitcnt lgkmcnt(0)
	s_barrier
	s_setprio 1
	s_waitcnt lgkmcnt(0)
	v_mfma_f32_16x16x32_bf16 v[68:71], v[56:59], v[186:189], v[68:71]
	v_mfma_f32_16x16x32_bf16 v[64:67], v[136:139], v[186:189], v[64:67]
	v_mfma_f32_16x16x32_bf16 v[44:47], v[56:59], v[198:201], v[44:47]
	v_mfma_f32_16x16x32_bf16 v[40:43], v[136:139], v[198:201], v[40:43]
	v_mfma_f32_16x16x32_bf16 v[28:31], v[56:59], v[206:209], v[28:31]
	v_mfma_f32_16x16x32_bf16 v[24:27], v[136:139], v[206:209], v[24:27]
	v_mfma_f32_16x16x32_bf16 v[12:15], v[56:59], v[214:217], v[12:15]
	v_mfma_f32_16x16x32_bf16 v[8:11], v[136:139], v[214:217], v[8:11]
	v_mfma_f32_16x16x32_bf16 v[68:71], v[60:63], v[194:197], v[68:71]
	v_mfma_f32_16x16x32_bf16 v[64:67], v[158:161], v[194:197], v[64:67]
	v_mfma_f32_16x16x32_bf16 v[44:47], v[60:63], v[202:205], v[44:47]
	v_mfma_f32_16x16x32_bf16 v[40:43], v[158:161], v[202:205], v[40:43]
	v_mfma_f32_16x16x32_bf16 v[28:31], v[60:63], v[210:213], v[28:31]
	v_mfma_f32_16x16x32_bf16 v[24:27], v[158:161], v[210:213], v[24:27]
	v_mfma_f32_16x16x32_bf16 v[12:15], v[60:63], v[218:221], v[12:15]
	v_mfma_f32_16x16x32_bf16 v[8:11], v[158:161], v[218:221], v[8:11]
	s_setprio 0
	s_setprio 1
	v_mfma_f32_16x16x32_bf16 v[52:55], v[170:173], v[186:189], v[52:55]
	v_mfma_f32_16x16x32_bf16 v[48:51], v[178:181], v[186:189], v[48:51]
	v_mfma_f32_16x16x32_bf16 v[36:39], v[170:173], v[198:201], v[36:39]
	v_mfma_f32_16x16x32_bf16 v[32:35], v[178:181], v[198:201], v[32:35]
	v_mfma_f32_16x16x32_bf16 v[20:23], v[170:173], v[206:209], v[20:23]
	v_mfma_f32_16x16x32_bf16 v[16:19], v[178:181], v[206:209], v[16:19]
	v_mfma_f32_16x16x32_bf16 v[4:7], v[170:173], v[214:217], v[4:7]
	v_mfma_f32_16x16x32_bf16 v[0:3], v[178:181], v[214:217], v[0:3]
	v_mfma_f32_16x16x32_bf16 v[52:55], v[174:177], v[194:197], v[52:55]
	v_mfma_f32_16x16x32_bf16 v[48:51], v[182:185], v[194:197], v[48:51]
	v_mfma_f32_16x16x32_bf16 v[36:39], v[174:177], v[202:205], v[36:39]
	v_mfma_f32_16x16x32_bf16 v[32:35], v[182:185], v[202:205], v[32:35]
	v_mfma_f32_16x16x32_bf16 v[20:23], v[174:177], v[210:213], v[20:23]
	v_mfma_f32_16x16x32_bf16 v[16:19], v[182:185], v[210:213], v[16:19]
	v_mfma_f32_16x16x32_bf16 v[4:7], v[174:177], v[218:221], v[4:7]
	v_mfma_f32_16x16x32_bf16 v[0:3], v[182:185], v[218:221], v[0:3]
	s_setprio 0
	s_barrier
	s_add_i32 s50, s50, 2
	s_add_u32 s24, s24, 0x100
	s_addc_u32 s25, s25, 0
	s_add_u32 s36, s36, 0x100
	s_addc_u32 s37, s37, 0
	s_cmp_gt_u32 s50, 13
	s_cbranch_scc0 .LBB0_119
	s_and_b64 vcc, exec, s[12:13]
	s_cbranch_vccz .LBB0_122
	s_barrier

; #define ATT_STAGE(t, buf) do { _Pragma("unroll") for (int i_ = 0; i_ < 2; ++i_) { \
;         glds16(Kt + (size_t)(t) * 131072, ksrc[i_], (unsigned)__builtin_amdgcn_readfirstlane(ldsb + KBUF + (buf) * 16384 + (w * 2 + i_) * 1024)); \
;         glds16(Vt + (size_t)(t) * 131072, vsrc[i_], (unsigned)__builtin_amdgcn_readfirstlane(ldsb + VBUF + (buf) * 16384 + (w * 2 + i_) * 1024)); } } while (0)
; __device__ __forceinline__ void attn_unit(ATT_LAS unsigned char* lds, const bf16_t* Qg, const bf16_t* Kg, const bf16_t* Vg, bf16_t* Og, int b, int head, int qb, float lam, const float* subg) {
;     ...
;         if (t + 1 < NT) ATT_STAGE(t + 1, buf ^ 1);
.Ldma_skip:
	s_and_b32 vcc_lo, s79, 1
	s_lshl_b32 vcc_lo, vcc_lo, 14
	s_add_i32 vcc_lo, vcc_lo, s77
	s_add_i32 m0, vcc_lo, 0x8000
	s_cmp_ge_u32 s79, s76
	s_cbranch_scc1 .Ldma_k2
	global_load_lds_dwordx4 v199, s[94:95]
.Ldma_k2:
	s_and_b32 vcc_lo, s79, 1
	s_lshl_b32 vcc_lo, vcc_lo, 14
	s_add_i32 m0, vcc_lo, s50
	s_cmp_ge_u32 s79, s76
	s_cbranch_scc1 .Ldma_k3
	global_load_lds_dwordx4 v200, s[92:93]
.Ldma_k3:
	s_and_b32 vcc_lo, s79, 1
	s_lshl_b32 vcc_lo, vcc_lo, 14
	s_add_i32 vcc_lo, vcc_lo, s50
	s_add_i32 m0, vcc_lo, 0x8000
	s_cmp_ge_u32 s79, s76
	s_cbranch_scc1 .Ldma_k4
	global_load_lds_dwordx4 v201, s[94:95]

; #define ATT_LAS __attribute__((address_space(3)))
; #define ATT_MFMA(a, b, c) __builtin_amdgcn_mfma_f32_32x32x16_bf16((a), (b), (c), 0, 0, 0)
; template <bool HAS_PV, bool HAS_QK, bool C1> ...
;     ...
;     if (HAS_QK) { const int ad = C1 ? sub1(kaddr[0]) : kaddr[0]; ka = *(const ATT_LAS bf16x8*)(kb + ad); qa = *(const ATT_LAS bf16x8*)(qb_ + ad);
; #pragma unroll
;         for (int i = 0; i < 16; ++i) Snext[i] = 0.f; }
;     float sa = 0.f, sb = 0.f;
; #pragma unroll
;     for (int g = 0; g < 4; ++g) {
;         s16x4 nlo[2], nhi[2]; bf16x8 nk, nq;
;         if (g < 3) {
;             if (HAS_PV) {
; #pragma unroll
;                 for (int u = 0; u < 2; ++u) { const int off = (2 * ((g + 1) & 1) + u) * 512 + ((g + 1) >> 1) * 4096; nlo[u] = vtr(vb + vaddr[0] + off); nhi[u] = vtr(vb + vaddr[1] + off); } }
;             if (HAS_QK) { const int ad = C1 ? sub1(kaddr[g + 1]) : kaddr[g + 1]; nk = *(const ATT_LAS bf16x8*)(kb + ad); nq = *(const ATT_LAS bf16x8*)(qb_ + ad); }
;         }
;         if (HAS_PV) { const bf16x8 pa = __builtin_bit_cast(bf16x8, pkin[g >> 1]);
; #pragma unroll
;             for (int u = 0; u < 2; ++u) { const bf16x8 vf = __builtin_shufflevector(vlo[u], vhi[u], 0, 1, 2, 3, 4, 5, 6, 7); Opv[2 * (g & 1) + u] = ATT_MFMA(pa, vf, Opv[2 * (g & 1) + u]); } }
;         if (HAS_QK) Snext = ATT_MFMA(ka, qa, Snext);
; #pragma unroll
;         for (int e = 4 * g; e < 4 * g + 4; e += 2) { Scur[e] = __builtin_amdgcn_exp2f(Scur[e] - m); Scur[e + 1] = __builtin_amdgcn_exp2f(Scur[e + 1] - m); sa += Scur[e]; sb += Scur[e + 1]; }
;         if (g & 1) pkout[g >> 1] = (u32x4){cvtpk(Scur[4 * g - 4], Scur[4 * g - 3]), cvtpk(Scur[4 * g - 2], Scur[4 * g - 1]), cvtpk(Scur[4 * g], Scur[4 * g + 1]), cvtpk(Scur[4 * g + 2], Scur[4 * g + 3])};
;         if (g < 3) {
;             if (HAS_PV) {
; #pragma unroll
;                 for (int u = 0; u < 2; ++u) { vlo[u] = nlo[u]; vhi[u] = nhi[u]; } }
;             if (HAS_QK) { ka = nk; qa = nq; }
;         }
;         __builtin_amdgcn_sched_barrier(0);
;     }
;     l += sa + sb;
;     return sa + sb;
; __device__ __forceinline__ void tile_body(bool MASK, const ATT_LAS unsigned char* kb, const ATT_LAS unsigned char* vb, const ATT_LAS unsigned char* qbase, const int (&kaddr)[4], const int (&vaddr)[2], ...
;     ...
;     if (__any(!(sm <= GUARD))) slow_step<false>(MASK, Sa, kb, qbase, kaddr, vaddr, O1, m1, l1, ls, kvrel, r, h, wsf, pkA);
.Lns_296:
	ds_read_b128 v[2:5], v248
	ds_read_b128 v[6:9], v244
	s_nop 1
	ds_read_b128 v[10:13], v249
	ds_read_b128 v[146:149], v245
	v_exp_f32_e32 v15, v170
	v_exp_f32_e32 v14, v171
	v_exp_f32_e32 v155, v172
	v_exp_f32_e32 v154, v173
	s_waitcnt lgkmcnt(2)
	v_mfma_f32_32x32x16_bf16 v[158:173], v[2:5], v[6:9], 0
	s_waitcnt lgkmcnt(0)
	v_mfma_f32_32x32x16_bf16 v[158:173], v[10:13], v[146:149], v[158:173]
	ds_read_b128 v[6:9], v250
	ds_read_b128 v[150:153], v246
	v_exp_f32_e32 v157, v174
	v_exp_f32_e32 v156, v175
	v_exp_f32_e32 v175, v176
	v_exp_f32_e32 v174, v177
	v_cvt_pk_bf16_f32 v2, v15, v14
	v_cvt_pk_bf16_f32 v3, v155, v154
	v_cvt_pk_bf16_f32 v4, v157, v156
	v_cvt_pk_bf16_f32 v5, v175, v174
	s_waitcnt lgkmcnt(0)
	v_mfma_f32_32x32x16_bf16 v[158:173], v[6:9], v[150:153], v[158:173]
	ds_read_b128 v[10:13], v251
	ds_read_b128 v[146:149], v247
	v_exp_f32_e32 v177, v178
	v_exp_f32_e32 v176, v179
	v_exp_f32_e32 v179, v180
	v_exp_f32_e32 v178, v181
	s_waitcnt lgkmcnt(0)
	v_mfma_f32_32x32x16_bf16 v[158:173], v[10:13], v[146:149], v[158:173]
	v_exp_f32_e32 v7, v182
	v_add_f32_e32 v14, v154, v14
	v_add_f32_e32 v15, v155, v15
	v_exp_f32_e32 v6, v183
	v_exp_f32_e32 v9, v184
	v_add_f32_e32 v14, v156, v14
	v_add_f32_e32 v15, v157, v15
	v_exp_f32_e32 v8, v185
	v_add_f32_e32 v14, v174, v14
	v_add_f32_e32 v15, v175, v15
	v_cvt_pk_bf16_f32 v10, v177, v176
	v_cvt_pk_bf16_f32 v11, v179, v178
	v_cvt_pk_bf16_f32 v12, v7, v6
	v_cvt_pk_bf16_f32 v13, v9, v8
	v_add_f32_e32 v14, v176, v14
	v_add_f32_e32 v15, v177, v15
	v_add_f32_e32 v14, v178, v14
	v_add_f32_e32 v15, v179, v15
	v_add_f32_e32 v6, v6, v14
	v_add_f32_e32 v7, v7, v15
	v_add_f32_e32 v6, v8, v6
	v_add_f32_e32 v7, v9, v7
	v_add_f32_e32 v6, v6, v7
	v_cmp_nge_f32_e32 vcc, s58, v6
	s_andn2_b64 s[4:5], exec, s[36:37]
	s_cbranch_vccz .Lns_305
	s_branch .Lslow_1

; #define PG8_STAGE(bufoff, gbase, voff) do { _Pragma("unroll") for (int _i = 0; _i < 2; ++_i) \
;         __builtin_amdgcn_global_load_lds((const unsigned*)((const char*)(gbase) + (voff)[_i]), (PG8_LAS unsigned*)(lds + (bufoff) + ldsw + _i * 8192), 16, 0, 0); } while (0)
; #define PG8_LDA(dst, b, h) do { _Pragma("unroll") for (int m = 0; m < 4; ++m) _Pragma("unroll") for (int k = 0; k < 2; ++k) dst[m][k] = *(const PG8_LAS bf16x8*)(lds + PG8_SA(b, h) + aoff + m * 2048 + k * 1024); } while (0)
; #define PG8_LDB(dst, b, h) do { _Pragma("unroll") for (int n = 0; n < 2; ++n) _Pragma("unroll") for (int k = 0; k < 2; ++k) dst[n][k] = *(const PG8_LAS bf16x8*)(lds + PG8_SB(b, h) + boff + n * 2048 + k * 1024); } while (0)
; #define PG8_SCHED __builtin_amdgcn_sched_barrier(0)
; template <class Epi, class Sched, bool ALIGN_EPI = false, bool SP2 = false>
; __device__ __forceinline__ void gemm_phase(PG8_LAS unsigned char* lds, const Gemm g, const Sched& S, const Epi& E) {
;     ...
;         const char* nA = has_next ? (const char*)g.A + (size_t)nxt.pm * tstep + (size_t)nxt.pn * g.a_pn_off : cA; const char* nB = has_next ? (const char*)g.Bt + (size_t)nxt.pn * tstep : cB;
;         for (int t = 0; t < nt; t += 2) {
;             const bool last = (t == nt - 2);
;             const char* a1 = cA + (size_t)(t + 1) * kstep;
;             const char* a2 = last ? nA : cA + (size_t)(t + 2) * kstep; const char* b2 = last ? nB : cB + (size_t)(t + 2) * kstep;
;             const char* a3 = a2 + kstep; const char* b3 = b2 + kstep;
;             if (last && has_next) S.a_ready(nxt);
;             if constexpr (SP2) {
;             PG8_LDB(B0, 0, 0); PG8_LDB(B1, 0, 1); PG8_SCHED; PG8_LDA(At, 0, 0); PG8_STAGE(PG8_SA(1, 1), a1 + hstep, voffA);
;     ...
;         for (int a = 0; a < 2; ++a)
; #pragma unroll
;             for (int b = 0; b < 2; ++b)
; #pragma unroll
;                 for (int m = 0; m < 4; ++m)
; #pragma unroll
;                     for (int n = 0; n < 2; ++n) acc[a][b][m][n] = (f32x4){0.f, 0.f, 0.f, 0.f};
.LBB0_412:
	s_ashr_i32 s23, s22, 31
	s_lshl_b64 s[24:25], s[22:23], 19
	s_add_u32 s24, s60, s24
	s_addc_u32 s25, s61, s25
	s_and_b64 s[26:27], s[6:7], exec
	s_cselect_b32 s23, s25, s35
	s_cselect_b32 s29, s24, s34
	s_ashr_i32 s21, s20, 31
	s_lshl_b64 s[26:27], s[20:21], 19
	s_add_u32 s26, s80, s26
	s_addc_u32 s27, s81, s27
	s_and_b64 s[40:41], s[6:7], exec
	s_cselect_b32 s21, s27, s37
	s_cselect_b32 s59, s26, s36
	s_add_u32 s34, s34, 0x40080
	s_addc_u32 s35, s35, 0
	s_add_u32 s62, s36, 0x100
	v_mov_b32_e32 v0, 0
	s_addc_u32 s63, s37, 0
	s_mov_b32 s64, -2
	v_mov_b32_e32 v1, v0
	v_mov_b32_e32 v2, v0
	v_mov_b32_e32 v3, v0
	v_mov_b32_e32 v4, v0
	v_mov_b32_e32 v5, v0
	v_mov_b32_e32 v6, v0
	v_mov_b32_e32 v7, v0
	v_mov_b32_e32 v16, v0
	v_mov_b32_e32 v17, v0
	v_mov_b32_e32 v18, v0
	v_mov_b32_e32 v19, v0
	v_mov_b32_e32 v20, v0
	v_mov_b32_e32 v21, v0
	v_mov_b32_e32 v22, v0
	v_mov_b32_e32 v23, v0
	v_mov_b32_e32 v32, v0
	v_mov_b32_e32 v33, v0
	v_mov_b32_e32 v34, v0
	v_mov_b32_e32 v35, v0
	v_mov_b32_e32 v36, v0
	v_mov_b32_e32 v37, v0
	v_mov_b32_e32 v38, v0
	v_mov_b32_e32 v39, v0
	v_mov_b32_e32 v48, v0
	v_mov_b32_e32 v49, v0
	v_mov_b32_e32 v50, v0
	v_mov_b32_e32 v51, v0
	v_mov_b32_e32 v52, v0
	v_mov_b32_e32 v53, v0
	v_mov_b32_e32 v54, v0
	v_mov_b32_e32 v55, v0
	v_mov_b32_e32 v8, v0
	v_mov_b32_e32 v9, v0
	v_mov_b32_e32 v10, v0
	v_mov_b32_e32 v11, v0
	v_mov_b32_e32 v12, v0
	v_mov_b32_e32 v13, v0
	v_mov_b32_e32 v14, v0
	v_mov_b32_e32 v15, v0
	v_mov_b32_e32 v24, v0
	v_mov_b32_e32 v25, v0
	v_mov_b32_e32 v26, v0
	v_mov_b32_e32 v27, v0
	v_mov_b32_e32 v28, v0
	v_mov_b32_e32 v29, v0
	v_mov_b32_e32 v30, v0
	v_mov_b32_e32 v31, v0
	v_mov_b32_e32 v40, v0
	v_mov_b32_e32 v41, v0
	v_mov_b32_e32 v42, v0
	v_mov_b32_e32 v43, v0
	v_mov_b32_e32 v44, v0
	v_mov_b32_e32 v45, v0
	v_mov_b32_e32 v46, v0
	v_mov_b32_e32 v47, v0
	v_mov_b32_e32 v56, v0
	v_mov_b32_e32 v57, v0
	v_mov_b32_e32 v58, v0
	v_mov_b32_e32 v59, v0
	v_mov_b32_e32 v60, v0
	v_mov_b32_e32 v61, v0
	v_mov_b32_e32 v62, v0
	v_mov_b32_e32 v63, v0
	v_mov_b32_e32 v64, v0
	v_mov_b32_e32 v65, v0
	v_mov_b32_e32 v66, v0
	v_mov_b32_e32 v67, v0
	v_mov_b32_e32 v68, v0
	v_mov_b32_e32 v69, v0
	v_mov_b32_e32 v70, v0
	v_mov_b32_e32 v71, v0
	v_mov_b32_e32 v80, v0
	v_mov_b32_e32 v81, v0
	v_mov_b32_e32 v82, v0
	v_mov_b32_e32 v83, v0
	v_mov_b32_e32 v84, v0
	v_mov_b32_e32 v85, v0
	v_mov_b32_e32 v86, v0
	v_mov_b32_e32 v87, v0
	v_mov_b32_e32 v96, v0
	v_mov_b32_e32 v97, v0
	v_mov_b32_e32 v98, v0
	v_mov_b32_e32 v99, v0
	v_mov_b32_e32 v100, v0
	v_mov_b32_e32 v101, v0
	v_mov_b32_e32 v102, v0
	v_mov_b32_e32 v103, v0
	v_mov_b32_e32 v112, v0
	v_mov_b32_e32 v113, v0
	v_mov_b32_e32 v114, v0
	v_mov_b32_e32 v115, v0
	v_mov_b32_e32 v116, v0
	v_mov_b32_e32 v117, v0
	v_mov_b32_e32 v118, v0
	v_mov_b32_e32 v119, v0
	v_mov_b32_e32 v72, v0
	v_mov_b32_e32 v73, v0
	v_mov_b32_e32 v74, v0
	v_mov_b32_e32 v75, v0
	v_mov_b32_e32 v76, v0
	v_mov_b32_e32 v77, v0
	v_mov_b32_e32 v78, v0
	v_mov_b32_e32 v79, v0
	v_mov_b32_e32 v88, v0
	v_mov_b32_e32 v89, v0
	v_mov_b32_e32 v90, v0
	v_mov_b32_e32 v91, v0
	v_mov_b32_e32 v92, v0
	v_mov_b32_e32 v93, v0
	v_mov_b32_e32 v94, v0
	v_mov_b32_e32 v95, v0
	v_mov_b32_e32 v104, v0
	v_mov_b32_e32 v105, v0
	v_mov_b32_e32 v106, v0
	v_mov_b32_e32 v107, v0
	v_mov_b32_e32 v108, v0
	v_mov_b32_e32 v109, v0
	v_mov_b32_e32 v110, v0
	v_mov_b32_e32 v111, v0
	v_mov_b32_e32 v120, v0
	v_mov_b32_e32 v121, v0
	v_mov_b32_e32 v122, v0
	v_mov_b32_e32 v123, v0
	v_mov_b32_e32 v124, v0
	v_mov_b32_e32 v125, v0
	v_mov_b32_e32 v126, v0
	v_mov_b32_e32 v127, v0
	v_add_u32_e32 v240, 0x18000, v149
	v_add_u32_e32 v241, 0x1c000, v149
.LBB0_413:
	ds_read_b128 v[144:147], v151
	ds_read_b128 v[154:157], v151 offset:1024
	ds_read_b128 v[158:161], v151 offset:2048
	ds_read_b128 v[162:165], v151 offset:3072
	ds_read_b128 v[166:169], v152
	ds_read_b128 v[170:173], v152 offset:1024
	ds_read_b128 v[174:177], v152 offset:2048
	ds_read_b128 v[178:181], v152 offset:3072
	s_add_u32 s36, s34, 0xfffc0080
	s_addc_u32 s37, s35, -1
	s_cmp_eq_u32 s64, 12
	s_cselect_b32 s41, s23, s37
	s_cselect_b32 s40, s29, s36
	s_cselect_b32 s37, s21, s63
	s_cselect_b32 s36, s59, s62
	s_add_u32 vcc_lo, s36, 0x80
	s_addc_u32 vcc_hi, s37, 0
	s_add_u32 s100, s40, 0x80
	s_addc_u32 s101, s41, 0
	s_add_i32 m0, s1, 0xc000
	ds_read_b128 v[182:185], v153
	ds_read_b128 v[186:189], v153 offset:1024
	ds_read_b128 v[194:197], v153 offset:2048
	ds_read_b128 v[198:201], v153 offset:3072
	ds_read_b128 v[202:205], v153 offset:4096
	ds_read_b128 v[206:209], v153 offset:5120
	ds_read_b128 v[210:213], v153 offset:6144
	global_load_lds_dwordx4 v136, s[34:35]
	s_add_i32 m0, s1, 0xe000
	ds_read_b128 v[214:217], v153 offset:7168
	global_load_lds_dwordx4 v138, s[34:35]
	s_waitcnt vmcnt(8)
	s_waitcnt lgkmcnt(0)
	s_barrier
; #define PG8_STAGE(bufoff, gbase, voff) do { _Pragma("unroll") for (int _i = 0; _i < 2; ++_i) \
;         __builtin_amdgcn_global_load_lds((const unsigned*)((const char*)(gbase) + (voff)[_i]), (PG8_LAS unsigned*)(lds + (bufoff) + ldsw + _i * 8192), 16, 0, 0); } while (0)
; #define PG8_LDA(dst, b, h) do { _Pragma("unroll") for (int m = 0; m < 4; ++m) _Pragma("unroll") for (int k = 0; k < 2; ++k) dst[m][k] = *(const PG8_LAS bf16x8*)(lds + PG8_SA(b, h) + aoff + m * 2048 + k * 1024); } while (0)
; #define PG8_MMA(ai, bj, At, Bt) do { __builtin_amdgcn_s_setprio(1); _Pragma("unroll") for (int m = 0; m < 4; ++m) _Pragma("unroll") for (int n = 0; n < 2; ++n) _Pragma("unroll") for (int k = 0; k < 2; ++k) \
;         acc[ai][bj][m][n] = __builtin_amdgcn_mfma_f32_16x16x32_bf16(Bt[n][k], At[m][k], acc[ai][bj][m][n], 0, 0, 0); __builtin_amdgcn_s_setprio(0); } while (0)
; #define PG8_WAIT_V(n) asm volatile("s_waitcnt vmcnt(" #n ")" ::: "memory")
; #define PG8_WAIT_L(n) asm volatile("s_waitcnt lgkmcnt(" #n ")" ::: "memory")
; #define PG8_BAR __builtin_amdgcn_s_barrier()
; #define PG8_SCHED __builtin_amdgcn_sched_barrier(0)
; template <class Epi, class Sched, bool ALIGN_EPI = false, bool SP2 = false>
; __device__ __forceinline__ void gemm_phase(PG8_LAS unsigned char* lds, const Gemm g, const Sched& S, const Epi& E) {
;     ...
;             PG8_WAIT_V(8); PG8_WAIT_L(0); PG8_BAR; PG8_MMA(0, 0, At, B0); PG8_MMA(0, 1, At, B1); PG8_BAR; PG8_SCHED;
;             PG8_LDA(At, 0, 1); PG8_STAGE(PG8_SB(0, 0), b2, voffB); PG8_STAGE(PG8_SB(0, 1), b2 + hstep, voffB); PG8_STAGE(PG8_SA(0, 0), a2, voffA);
;             PG8_WAIT_V(8); PG8_WAIT_L(0); PG8_BAR; PG8_MMA(1, 0, At, B0); PG8_MMA(1, 1, At, B1); PG8_BAR; PG8_SCHED;
	s_setprio 1
	s_waitcnt lgkmcnt(0)
	v_mfma_f32_16x16x32_bf16 v[124:127], v[144:147], v[182:185], v[124:127]
	v_mfma_f32_16x16x32_bf16 v[120:123], v[158:161], v[182:185], v[120:123]
	v_mfma_f32_16x16x32_bf16 v[108:111], v[144:147], v[194:197], v[108:111]
	v_mfma_f32_16x16x32_bf16 v[104:107], v[158:161], v[194:197], v[104:107]
	v_mfma_f32_16x16x32_bf16 v[92:95], v[144:147], v[202:205], v[92:95]
	v_mfma_f32_16x16x32_bf16 v[88:91], v[158:161], v[202:205], v[88:91]
	v_mfma_f32_16x16x32_bf16 v[76:79], v[144:147], v[210:213], v[76:79]
	v_mfma_f32_16x16x32_bf16 v[72:75], v[158:161], v[210:213], v[72:75]
	v_mfma_f32_16x16x32_bf16 v[124:127], v[154:157], v[186:189], v[124:127]
	v_mfma_f32_16x16x32_bf16 v[120:123], v[162:165], v[186:189], v[120:123]
	v_mfma_f32_16x16x32_bf16 v[108:111], v[154:157], v[198:201], v[108:111]
	v_mfma_f32_16x16x32_bf16 v[104:107], v[162:165], v[198:201], v[104:107]
	v_mfma_f32_16x16x32_bf16 v[92:95], v[154:157], v[206:209], v[92:95]
	v_mfma_f32_16x16x32_bf16 v[88:91], v[162:165], v[206:209], v[88:91]
	v_mfma_f32_16x16x32_bf16 v[76:79], v[154:157], v[214:217], v[76:79]
	v_mfma_f32_16x16x32_bf16 v[72:75], v[162:165], v[214:217], v[72:75]
	s_setprio 0
	s_setprio 1
	v_mfma_f32_16x16x32_bf16 v[116:119], v[166:169], v[182:185], v[116:119]
	v_mfma_f32_16x16x32_bf16 v[112:115], v[174:177], v[182:185], v[112:115]
	v_mfma_f32_16x16x32_bf16 v[100:103], v[166:169], v[194:197], v[100:103]
	v_mfma_f32_16x16x32_bf16 v[96:99], v[174:177], v[194:197], v[96:99]
	v_mfma_f32_16x16x32_bf16 v[84:87], v[166:169], v[202:205], v[84:87]
	v_mfma_f32_16x16x32_bf16 v[80:83], v[174:177], v[202:205], v[80:83]
	v_mfma_f32_16x16x32_bf16 v[68:71], v[166:169], v[210:213], v[68:71]
	v_mfma_f32_16x16x32_bf16 v[64:67], v[174:177], v[210:213], v[64:67]
	v_mfma_f32_16x16x32_bf16 v[116:119], v[170:173], v[186:189], v[116:119]
	v_mfma_f32_16x16x32_bf16 v[112:115], v[178:181], v[186:189], v[112:115]
	v_mfma_f32_16x16x32_bf16 v[100:103], v[170:173], v[198:201], v[100:103]
	v_mfma_f32_16x16x32_bf16 v[96:99], v[178:181], v[198:201], v[96:99]
	v_mfma_f32_16x16x32_bf16 v[84:87], v[170:173], v[206:209], v[84:87]
	v_mfma_f32_16x16x32_bf16 v[80:83], v[178:181], v[206:209], v[80:83]
	v_mfma_f32_16x16x32_bf16 v[68:71], v[170:173], v[214:217], v[68:71]
	v_mfma_f32_16x16x32_bf16 v[64:67], v[178:181], v[214:217], v[64:67]
	s_setprio 0
	s_barrier
	s_add_i32 s65, s50, s0
	s_mov_b32 m0, s65
	ds_read_b128 v[182:185], v153 offset:16384
	ds_read_b128 v[186:189], v153 offset:17408
	ds_read_b128 v[194:197], v153 offset:18432
	ds_read_b128 v[198:201], v153 offset:19456
	global_load_lds_dwordx4 v130, s[36:37]
	s_add_i32 m0, s65, 0x2000
	s_add_u32 s66, s36, 0x40000
	s_addc_u32 s67, s37, 0
	s_add_i32 s65, s51, s0
	global_load_lds_dwordx4 v134, s[36:37]
	s_mov_b32 m0, s65
	ds_read_b128 v[214:217], v153 offset:23552
	global_load_lds_dwordx4 v130, s[66:67]
	s_add_i32 m0, s65, 0x2000
	ds_read_b128 v[210:213], v153 offset:22528
	global_load_lds_dwordx4 v134, s[66:67]
	s_mov_b32 m0, s1
	ds_read_b128 v[206:209], v153 offset:21504
	global_load_lds_dwordx4 v128, s[40:41]
	s_mov_b32 m0, s31
	ds_read_b128 v[202:205], v153 offset:20480
	global_load_lds_dwordx4 v132, s[40:41]
	s_waitcnt vmcnt(8)
	s_waitcnt lgkmcnt(0)
	s_barrier
	s_setprio 1
	s_waitcnt lgkmcnt(0)
	v_mfma_f32_16x16x32_bf16 v[60:63], v[144:147], v[182:185], v[60:63]
	v_mfma_f32_16x16x32_bf16 v[56:59], v[158:161], v[182:185], v[56:59]
	v_mfma_f32_16x16x32_bf16 v[44:47], v[144:147], v[194:197], v[44:47]
	v_mfma_f32_16x16x32_bf16 v[40:43], v[158:161], v[194:197], v[40:43]
	v_mfma_f32_16x16x32_bf16 v[28:31], v[144:147], v[202:205], v[28:31]
	v_mfma_f32_16x16x32_bf16 v[24:27], v[158:161], v[202:205], v[24:27]
	v_mfma_f32_16x16x32_bf16 v[12:15], v[144:147], v[210:213], v[12:15]
	v_mfma_f32_16x16x32_bf16 v[8:11], v[158:161], v[210:213], v[8:11]
	v_mfma_f32_16x16x32_bf16 v[60:63], v[154:157], v[186:189], v[60:63]
	v_mfma_f32_16x16x32_bf16 v[56:59], v[162:165], v[186:189], v[56:59]
	v_mfma_f32_16x16x32_bf16 v[44:47], v[154:157], v[198:201], v[44:47]
	v_mfma_f32_16x16x32_bf16 v[40:43], v[162:165], v[198:201], v[40:43]
	v_mfma_f32_16x16x32_bf16 v[28:31], v[154:157], v[206:209], v[28:31]
	v_mfma_f32_16x16x32_bf16 v[24:27], v[162:165], v[206:209], v[24:27]
	v_mfma_f32_16x16x32_bf16 v[12:15], v[154:157], v[214:217], v[12:15]
	v_mfma_f32_16x16x32_bf16 v[8:11], v[162:165], v[214:217], v[8:11]
	s_setprio 0
	s_setprio 1
	v_mfma_f32_16x16x32_bf16 v[52:55], v[166:169], v[182:185], v[52:55]
	v_mfma_f32_16x16x32_bf16 v[48:51], v[174:177], v[182:185], v[48:51]
	v_mfma_f32_16x16x32_bf16 v[36:39], v[166:169], v[194:197], v[36:39]
	v_mfma_f32_16x16x32_bf16 v[32:35], v[174:177], v[194:197], v[32:35]
	v_mfma_f32_16x16x32_bf16 v[20:23], v[166:169], v[202:205], v[20:23]
	v_mfma_f32_16x16x32_bf16 v[16:19], v[174:177], v[202:205], v[16:19]
	v_mfma_f32_16x16x32_bf16 v[4:7], v[166:169], v[210:213], v[4:7]
	v_mfma_f32_16x16x32_bf16 v[0:3], v[174:177], v[210:213], v[0:3]
	v_mfma_f32_16x16x32_bf16 v[52:55], v[170:173], v[186:189], v[52:55]
	v_mfma_f32_16x16x32_bf16 v[48:51], v[178:181], v[186:189], v[48:51]
	v_mfma_f32_16x16x32_bf16 v[36:39], v[170:173], v[198:201], v[36:39]
	v_mfma_f32_16x16x32_bf16 v[32:35], v[178:181], v[198:201], v[32:35]
	v_mfma_f32_16x16x32_bf16 v[20:23], v[170:173], v[206:209], v[20:23]
	v_mfma_f32_16x16x32_bf16 v[16:19], v[178:181], v[206:209], v[16:19]
	v_mfma_f32_16x16x32_bf16 v[4:7], v[170:173], v[214:217], v[4:7]
	v_mfma_f32_16x16x32_bf16 v[0:3], v[178:181], v[214:217], v[0:3]
	s_setprio 0
	s_barrier
; #define PG8_STAGE(bufoff, gbase, voff) do { _Pragma("unroll") for (int _i = 0; _i < 2; ++_i) \
;         __builtin_amdgcn_global_load_lds((const unsigned*)((const char*)(gbase) + (voff)[_i]), (PG8_LAS unsigned*)(lds + (bufoff) + ldsw + _i * 8192), 16, 0, 0); } while (0)
; #define PG8_LDA(dst, b, h) do { _Pragma("unroll") for (int m = 0; m < 4; ++m) _Pragma("unroll") for (int k = 0; k < 2; ++k) dst[m][k] = *(const PG8_LAS bf16x8*)(lds + PG8_SA(b, h) + aoff + m * 2048 + k * 1024); } while (0)
; #define PG8_LDB(dst, b, h) do { _Pragma("unroll") for (int n = 0; n < 2; ++n) _Pragma("unroll") for (int k = 0; k < 2; ++k) dst[n][k] = *(const PG8_LAS bf16x8*)(lds + PG8_SB(b, h) + boff + n * 2048 + k * 1024); } while (0)
; template <class Epi, class Sched, bool ALIGN_EPI = false, bool SP2 = false>
; __device__ __forceinline__ void gemm_phase(PG8_LAS unsigned char* lds, const Gemm g, const Sched& S, const Epi& E) {
;     ...
;         for (int t = 0; t < nt; t += 2) {
;             const bool last = (t == nt - 2);
;             const char* a1 = cA + (size_t)(t + 1) * kstep;
;             const char* a2 = last ? nA : cA + (size_t)(t + 2) * kstep; const char* b2 = last ? nB : cB + (size_t)(t + 2) * kstep;
;             const char* a3 = a2 + kstep; const char* b3 = b2 + kstep;
;             if (last && has_next) S.a_ready(nxt);
;             if constexpr (SP2) {
;             PG8_LDB(B0, 0, 0); PG8_LDB(B1, 0, 1); PG8_SCHED; PG8_LDA(At, 0, 0); PG8_STAGE(PG8_SA(1, 1), a1 + hstep, voffA);
;             PG8_WAIT_V(8); PG8_WAIT_L(0); PG8_BAR; PG8_MMA(0, 0, At, B0); PG8_MMA(0, 1, At, B1); PG8_BAR; PG8_SCHED;
;             PG8_LDA(At, 0, 1); PG8_STAGE(PG8_SB(0, 0), b2, voffB); PG8_STAGE(PG8_SB(0, 1), b2 + hstep, voffB); PG8_STAGE(PG8_SA(0, 0), a2, voffA);
;             PG8_WAIT_V(8); PG8_WAIT_L(0); PG8_BAR; PG8_MMA(1, 0, At, B0); PG8_MMA(1, 1, At, B1); PG8_BAR; PG8_SCHED;
;             PG8_LDB(B0, 1, 0); PG8_LDB(B1, 1, 1); PG8_SCHED; PG8_LDA(At, 1, 0); PG8_STAGE(PG8_SA(0, 1), a2 + hstep, voffA);
;             PG8_WAIT_V(8); PG8_WAIT_L(0); PG8_BAR; PG8_MMA(0, 0, At, B0); PG8_MMA(0, 1, At, B1); PG8_BAR; PG8_SCHED;
;             PG8_LDA(At, 1, 1); PG8_STAGE(PG8_SB(1, 0), b3, voffB); PG8_STAGE(PG8_SB(1, 1), b3 + hstep, voffB); PG8_STAGE(PG8_SA(1, 0), a3, voffA);
;             PG8_WAIT_V(8); PG8_WAIT_L(0); PG8_BAR; PG8_MMA(1, 0, At, B0); PG8_MMA(1, 1, At, B1); PG8_BAR; PG8_SCHED;
	s_add_i32 s65, 0, 0x18000
	s_add_i32 s66, 0, 0x1c000
	ds_read_b128 v[144:147], v240
	ds_read_b128 v[154:157], v240 offset:1024
	ds_read_b128 v[158:161], v240 offset:2048
	ds_read_b128 v[162:165], v240 offset:3072
	ds_read_b128 v[166:169], v241
	ds_read_b128 v[170:173], v241 offset:1024
	ds_read_b128 v[174:177], v241 offset:2048
	ds_read_b128 v[178:181], v241 offset:3072
	s_add_u32 s40, s40, 0x40000
	s_addc_u32 s41, s41, 0
	s_mov_b32 m0, s38
	ds_read_b128 v[182:185], v153 offset:32768
	ds_read_b128 v[186:189], v153 offset:33792
	ds_read_b128 v[194:197], v153 offset:34816
	ds_read_b128 v[198:201], v153 offset:35840
	ds_read_b128 v[202:205], v153 offset:36864
	ds_read_b128 v[206:209], v153 offset:37888
	ds_read_b128 v[210:213], v153 offset:38912
	global_load_lds_dwordx4 v128, s[40:41]
	s_mov_b32 m0, s39
	ds_read_b128 v[214:217], v153 offset:39936
	global_load_lds_dwordx4 v132, s[40:41]
	s_waitcnt vmcnt(8)
	s_waitcnt lgkmcnt(0)
	s_barrier
	s_setprio 1
	s_waitcnt lgkmcnt(0)
	v_mfma_f32_16x16x32_bf16 v[124:127], v[144:147], v[182:185], v[124:127]
	v_mfma_f32_16x16x32_bf16 v[120:123], v[158:161], v[182:185], v[120:123]
	v_mfma_f32_16x16x32_bf16 v[108:111], v[144:147], v[194:197], v[108:111]
	v_mfma_f32_16x16x32_bf16 v[104:107], v[158:161], v[194:197], v[104:107]
	v_mfma_f32_16x16x32_bf16 v[92:95], v[144:147], v[202:205], v[92:95]
	v_mfma_f32_16x16x32_bf16 v[88:91], v[158:161], v[202:205], v[88:91]
	v_mfma_f32_16x16x32_bf16 v[76:79], v[144:147], v[210:213], v[76:79]
	v_mfma_f32_16x16x32_bf16 v[72:75], v[158:161], v[210:213], v[72:75]
	v_mfma_f32_16x16x32_bf16 v[124:127], v[154:157], v[186:189], v[124:127]
	v_mfma_f32_16x16x32_bf16 v[120:123], v[162:165], v[186:189], v[120:123]
	v_mfma_f32_16x16x32_bf16 v[108:111], v[154:157], v[198:201], v[108:111]
	v_mfma_f32_16x16x32_bf16 v[104:107], v[162:165], v[198:201], v[104:107]
	v_mfma_f32_16x16x32_bf16 v[92:95], v[154:157], v[206:209], v[92:95]
	v_mfma_f32_16x16x32_bf16 v[88:91], v[162:165], v[206:209], v[88:91]
	v_mfma_f32_16x16x32_bf16 v[76:79], v[154:157], v[214:217], v[76:79]
	v_mfma_f32_16x16x32_bf16 v[72:75], v[162:165], v[214:217], v[72:75]
	s_setprio 0
	s_setprio 1
	v_mfma_f32_16x16x32_bf16 v[116:119], v[166:169], v[182:185], v[116:119]
	v_mfma_f32_16x16x32_bf16 v[112:115], v[174:177], v[182:185], v[112:115]
	v_mfma_f32_16x16x32_bf16 v[100:103], v[166:169], v[194:197], v[100:103]
	v_mfma_f32_16x16x32_bf16 v[96:99], v[174:177], v[194:197], v[96:99]
	v_mfma_f32_16x16x32_bf16 v[84:87], v[166:169], v[202:205], v[84:87]
	v_mfma_f32_16x16x32_bf16 v[80:83], v[174:177], v[202:205], v[80:83]
	v_mfma_f32_16x16x32_bf16 v[68:71], v[166:169], v[210:213], v[68:71]
	v_mfma_f32_16x16x32_bf16 v[64:67], v[174:177], v[210:213], v[64:67]
	v_mfma_f32_16x16x32_bf16 v[116:119], v[170:173], v[186:189], v[116:119]
	v_mfma_f32_16x16x32_bf16 v[112:115], v[178:181], v[186:189], v[112:115]
	v_mfma_f32_16x16x32_bf16 v[100:103], v[170:173], v[198:201], v[100:103]
	v_mfma_f32_16x16x32_bf16 v[96:99], v[178:181], v[198:201], v[96:99]
	v_mfma_f32_16x16x32_bf16 v[84:87], v[170:173], v[206:209], v[84:87]
	v_mfma_f32_16x16x32_bf16 v[80:83], v[178:181], v[206:209], v[80:83]
	v_mfma_f32_16x16x32_bf16 v[68:71], v[170:173], v[214:217], v[68:71]
	v_mfma_f32_16x16x32_bf16 v[64:67], v[178:181], v[214:217], v[64:67]
	s_setprio 0
	s_barrier
	s_add_i32 s40, s65, s0
	s_mov_b32 m0, s40
	ds_read_b128 v[182:185], v153 offset:49152
	ds_read_b128 v[186:189], v153 offset:50176
	ds_read_b128 v[194:197], v153 offset:51200
	ds_read_b128 v[198:201], v153 offset:52224
	global_load_lds_dwordx4 v130, vcc
	s_add_i32 m0, s40, 0x2000
	s_add_u32 s36, s36, 0x40080
	s_addc_u32 s37, s37, 0
	s_add_i32 s40, s66, s0
	global_load_lds_dwordx4 v134, vcc
	s_mov_b32 m0, s40
	ds_read_b128 v[214:217], v153 offset:56320
	global_load_lds_dwordx4 v130, s[36:37]
	s_add_i32 m0, s40, 0x2000
	ds_read_b128 v[210:213], v153 offset:55296
	global_load_lds_dwordx4 v134, s[36:37]
	s_mov_b32 m0, s44
	ds_read_b128 v[206:209], v153 offset:54272
	global_load_lds_dwordx4 v128, s[100:101]
	s_mov_b32 m0, s45
	ds_read_b128 v[202:205], v153 offset:53248
	global_load_lds_dwordx4 v132, s[100:101]
	s_waitcnt vmcnt(8)
	s_waitcnt lgkmcnt(0)
	s_barrier
	s_setprio 1
	s_waitcnt lgkmcnt(0)
	v_mfma_f32_16x16x32_bf16 v[60:63], v[144:147], v[182:185], v[60:63]
	v_mfma_f32_16x16x32_bf16 v[56:59], v[158:161], v[182:185], v[56:59]
	v_mfma_f32_16x16x32_bf16 v[44:47], v[144:147], v[194:197], v[44:47]
	v_mfma_f32_16x16x32_bf16 v[40:43], v[158:161], v[194:197], v[40:43]
	v_mfma_f32_16x16x32_bf16 v[28:31], v[144:147], v[202:205], v[28:31]
	v_mfma_f32_16x16x32_bf16 v[24:27], v[158:161], v[202:205], v[24:27]
	v_mfma_f32_16x16x32_bf16 v[12:15], v[144:147], v[210:213], v[12:15]
	v_mfma_f32_16x16x32_bf16 v[8:11], v[158:161], v[210:213], v[8:11]
	v_mfma_f32_16x16x32_bf16 v[60:63], v[154:157], v[186:189], v[60:63]
	v_mfma_f32_16x16x32_bf16 v[56:59], v[162:165], v[186:189], v[56:59]
	v_mfma_f32_16x16x32_bf16 v[44:47], v[154:157], v[198:201], v[44:47]
	v_mfma_f32_16x16x32_bf16 v[40:43], v[162:165], v[198:201], v[40:43]
	v_mfma_f32_16x16x32_bf16 v[28:31], v[154:157], v[206:209], v[28:31]
	v_mfma_f32_16x16x32_bf16 v[24:27], v[162:165], v[206:209], v[24:27]
	v_mfma_f32_16x16x32_bf16 v[12:15], v[154:157], v[214:217], v[12:15]
	v_mfma_f32_16x16x32_bf16 v[8:11], v[162:165], v[214:217], v[8:11]
	s_setprio 0
	s_setprio 1
	v_mfma_f32_16x16x32_bf16 v[52:55], v[166:169], v[182:185], v[52:55]
	v_mfma_f32_16x16x32_bf16 v[48:51], v[174:177], v[182:185], v[48:51]
	v_mfma_f32_16x16x32_bf16 v[36:39], v[166:169], v[194:197], v[36:39]
	v_mfma_f32_16x16x32_bf16 v[32:35], v[174:177], v[194:197], v[32:35]
	v_mfma_f32_16x16x32_bf16 v[20:23], v[166:169], v[202:205], v[20:23]
	v_mfma_f32_16x16x32_bf16 v[16:19], v[174:177], v[202:205], v[16:19]
	v_mfma_f32_16x16x32_bf16 v[4:7], v[166:169], v[210:213], v[4:7]
	v_mfma_f32_16x16x32_bf16 v[0:3], v[174:177], v[210:213], v[0:3]
	v_mfma_f32_16x16x32_bf16 v[52:55], v[170:173], v[186:189], v[52:55]
	v_mfma_f32_16x16x32_bf16 v[48:51], v[178:181], v[186:189], v[48:51]
	v_mfma_f32_16x16x32_bf16 v[36:39], v[170:173], v[198:201], v[36:39]
	v_mfma_f32_16x16x32_bf16 v[32:35], v[178:181], v[198:201], v[32:35]
	v_mfma_f32_16x16x32_bf16 v[20:23], v[170:173], v[206:209], v[20:23]
	v_mfma_f32_16x16x32_bf16 v[16:19], v[178:181], v[206:209], v[16:19]
	v_mfma_f32_16x16x32_bf16 v[4:7], v[170:173], v[214:217], v[4:7]
	v_mfma_f32_16x16x32_bf16 v[0:3], v[178:181], v[214:217], v[0:3]
	s_setprio 0
	s_barrier
	s_add_i32 s64, s64, 2
	s_add_u32 s34, s34, 0x100
	s_addc_u32 s35, s35, 0
	s_add_u32 s62, s62, 0x100
	s_addc_u32 s63, s63, 0
	s_cmp_gt_u32 s64, 13
	s_cbranch_scc0 .LBB0_413
	s_and_b64 vcc, exec, s[18:19]
	s_cbranch_vccz .LBB0_416
	s_barrier

; #define PG8_STAGE(bufoff, gbase, voff) do { _Pragma("unroll") for (int _i = 0; _i < 2; ++_i) \
;         __builtin_amdgcn_global_load_lds((const unsigned*)((const char*)(gbase) + (voff)[_i]), (PG8_LAS unsigned*)(lds + (bufoff) + ldsw + _i * 8192), 16, 0, 0); } while (0)
; #define PG8_LDA(dst, b, h) do { _Pragma("unroll") for (int m = 0; m < 4; ++m) _Pragma("unroll") for (int k = 0; k < 2; ++k) dst[m][k] = *(const PG8_LAS bf16x8*)(lds + PG8_SA(b, h) + aoff + m * 2048 + k * 1024); } while (0)
; #define PG8_LDB(dst, b, h) do { _Pragma("unroll") for (int n = 0; n < 2; ++n) _Pragma("unroll") for (int k = 0; k < 2; ++k) dst[n][k] = *(const PG8_LAS bf16x8*)(lds + PG8_SB(b, h) + boff + n * 2048 + k * 1024); } while (0)
; #define PG8_WAIT_V(n) asm volatile("s_waitcnt vmcnt(" #n ")" ::: "memory")
; #define PG8_WAIT_L(n) asm volatile("s_waitcnt lgkmcnt(" #n ")" ::: "memory")
; #define PG8_BAR __builtin_amdgcn_s_barrier()
; template <class Epi, class Sched, bool ALIGN_EPI = false, bool SP2 = false>
; __device__ __forceinline__ void gemm_phase(PG8_LAS unsigned char* lds, const Gemm g, const Sched& S, const Epi& E) {
;     ...
;         const bool has_next = S.next(ui + 1, nxt);
;         const char* nA = has_next ? (const char*)g.A + (size_t)nxt.pm * tstep + (size_t)nxt.pn * g.a_pn_off : cA; const char* nB = has_next ? (const char*)g.Bt + (size_t)nxt.pn * tstep : cB;
;         for (int t = 0; t < nt; t += 2) {
;             const bool last = (t == nt - 2);
;             const char* a1 = cA + (size_t)(t + 1) * kstep;
;             const char* a2 = last ? nA : cA + (size_t)(t + 2) * kstep; const char* b2 = last ? nB : cB + (size_t)(t + 2) * kstep;
;             const char* a3 = a2 + kstep; const char* b3 = b2 + kstep;
;             if (last && has_next) S.a_ready(nxt);
;             if constexpr (SP2) {
;             PG8_LDB(B0, 0, 0); PG8_LDB(B1, 0, 1); PG8_SCHED; PG8_LDA(At, 0, 0); PG8_STAGE(PG8_SA(1, 1), a1 + hstep, voffA);
;             PG8_WAIT_V(8); PG8_WAIT_L(0); PG8_BAR; PG8_MMA(0, 0, At, B0); PG8_MMA(0, 1, At, B1); PG8_BAR; PG8_SCHED;
;     ...
; #pragma unroll
;         for (int a = 0; a < 2; ++a)
; #pragma unroll
;             for (int b = 0; b < 2; ++b)
; #pragma unroll
;                 for (int m = 0; m < 4; ++m)
; #pragma unroll
;                     for (int n = 0; n < 2; ++n) acc[a][b][m][n] = (f32x4){0.f, 0.f, 0.f, 0.f};
;         cur = nxt; cA = nA; cB = nB; ++ui;
.LBB0_461:
	s_ashr_i32 s17, s16, 31
	s_lshl_b64 s[18:19], s[16:17], 19
	s_add_u32 s18, s46, s18
	s_addc_u32 s19, s47, s19
	s_and_b64 s[20:21], s[4:5], exec
	s_cselect_b32 s17, s19, s25
	s_cselect_b32 s41, s18, s24
	s_ashr_i32 s11, s10, 31
	s_lshl_b64 s[20:21], s[10:11], 19
	s_add_u32 s20, s78, s20
	s_addc_u32 s21, s79, s21
	s_and_b64 s[28:29], s[4:5], exec
	s_cselect_b32 s11, s21, s27
	s_cselect_b32 s42, s20, s26
	s_add_u32 s24, s24, 0x40080
	s_addc_u32 s25, s25, 0
	s_add_u32 s44, s26, 0x100
	v_mov_b32_e32 v0, 0
	s_addc_u32 s45, s27, 0
	s_mov_b32 s50, -2
	v_mov_b32_e32 v1, v0
	v_mov_b32_e32 v2, v0
	v_mov_b32_e32 v3, v0
	v_mov_b32_e32 v4, v0
	v_mov_b32_e32 v5, v0
	v_mov_b32_e32 v6, v0
	v_mov_b32_e32 v7, v0
	v_mov_b32_e32 v16, v0
	v_mov_b32_e32 v17, v0
	v_mov_b32_e32 v18, v0
	v_mov_b32_e32 v19, v0
	v_mov_b32_e32 v20, v0
	v_mov_b32_e32 v21, v0
	v_mov_b32_e32 v22, v0
	v_mov_b32_e32 v23, v0
	v_mov_b32_e32 v32, v0
	v_mov_b32_e32 v33, v0
	v_mov_b32_e32 v34, v0
	v_mov_b32_e32 v35, v0
	v_mov_b32_e32 v36, v0
	v_mov_b32_e32 v37, v0
	v_mov_b32_e32 v38, v0
	v_mov_b32_e32 v39, v0
	v_mov_b32_e32 v48, v0
	v_mov_b32_e32 v49, v0
	v_mov_b32_e32 v50, v0
	v_mov_b32_e32 v51, v0
	v_mov_b32_e32 v52, v0
	v_mov_b32_e32 v53, v0
	v_mov_b32_e32 v54, v0
	v_mov_b32_e32 v55, v0
	v_mov_b32_e32 v8, v0
	v_mov_b32_e32 v9, v0
	v_mov_b32_e32 v10, v0
	v_mov_b32_e32 v11, v0
	v_mov_b32_e32 v12, v0
	v_mov_b32_e32 v13, v0
	v_mov_b32_e32 v14, v0
	v_mov_b32_e32 v15, v0
	v_mov_b32_e32 v24, v0
	v_mov_b32_e32 v25, v0
	v_mov_b32_e32 v26, v0
	v_mov_b32_e32 v27, v0
	v_mov_b32_e32 v28, v0
	v_mov_b32_e32 v29, v0
	v_mov_b32_e32 v30, v0
	v_mov_b32_e32 v31, v0
	v_mov_b32_e32 v40, v0
	v_mov_b32_e32 v41, v0
	v_mov_b32_e32 v42, v0
	v_mov_b32_e32 v43, v0
	v_mov_b32_e32 v44, v0
	v_mov_b32_e32 v45, v0
	v_mov_b32_e32 v46, v0
	v_mov_b32_e32 v47, v0
	v_mov_b32_e32 v56, v0
	v_mov_b32_e32 v57, v0
	v_mov_b32_e32 v58, v0
	v_mov_b32_e32 v59, v0
	v_mov_b32_e32 v60, v0
	v_mov_b32_e32 v61, v0
	v_mov_b32_e32 v62, v0
	v_mov_b32_e32 v63, v0
	v_mov_b32_e32 v64, v0
	v_mov_b32_e32 v65, v0
	v_mov_b32_e32 v66, v0
	v_mov_b32_e32 v67, v0
	v_mov_b32_e32 v68, v0
	v_mov_b32_e32 v69, v0
	v_mov_b32_e32 v70, v0
	v_mov_b32_e32 v71, v0
	v_mov_b32_e32 v80, v0
	v_mov_b32_e32 v81, v0
	v_mov_b32_e32 v82, v0
	v_mov_b32_e32 v83, v0
	v_mov_b32_e32 v84, v0
	v_mov_b32_e32 v85, v0
	v_mov_b32_e32 v86, v0
	v_mov_b32_e32 v87, v0
	v_mov_b32_e32 v96, v0
	v_mov_b32_e32 v97, v0
	v_mov_b32_e32 v98, v0
	v_mov_b32_e32 v99, v0
	v_mov_b32_e32 v100, v0
	v_mov_b32_e32 v101, v0
	v_mov_b32_e32 v102, v0
	v_mov_b32_e32 v103, v0
	v_mov_b32_e32 v112, v0
	v_mov_b32_e32 v113, v0
	v_mov_b32_e32 v114, v0
	v_mov_b32_e32 v115, v0
	v_mov_b32_e32 v116, v0
	v_mov_b32_e32 v117, v0
	v_mov_b32_e32 v118, v0
	v_mov_b32_e32 v119, v0
	v_mov_b32_e32 v72, v0
	v_mov_b32_e32 v73, v0
	v_mov_b32_e32 v74, v0
	v_mov_b32_e32 v75, v0
	v_mov_b32_e32 v76, v0
	v_mov_b32_e32 v77, v0
	v_mov_b32_e32 v78, v0
	v_mov_b32_e32 v79, v0
	v_mov_b32_e32 v88, v0
	v_mov_b32_e32 v89, v0
	v_mov_b32_e32 v90, v0
	v_mov_b32_e32 v91, v0
	v_mov_b32_e32 v92, v0
	v_mov_b32_e32 v93, v0
	v_mov_b32_e32 v94, v0
	v_mov_b32_e32 v95, v0
	v_mov_b32_e32 v104, v0
	v_mov_b32_e32 v105, v0
	v_mov_b32_e32 v106, v0
	v_mov_b32_e32 v107, v0
	v_mov_b32_e32 v108, v0
	v_mov_b32_e32 v109, v0
	v_mov_b32_e32 v110, v0
	v_mov_b32_e32 v111, v0
	v_mov_b32_e32 v120, v0
	v_mov_b32_e32 v121, v0
	v_mov_b32_e32 v122, v0
	v_mov_b32_e32 v123, v0
	v_mov_b32_e32 v124, v0
	v_mov_b32_e32 v125, v0
	v_mov_b32_e32 v126, v0
	v_mov_b32_e32 v127, v0
	v_add_u32_e32 v240, 0x18000, v149
	v_add_u32_e32 v241, 0x1c000, v149
.LBB0_462:
	ds_read_b128 v[156:159], v151
	ds_read_b128 v[160:163], v151 offset:1024
	ds_read_b128 v[164:167], v151 offset:2048
	ds_read_b128 v[168:171], v151 offset:3072
	ds_read_b128 v[172:175], v152
	ds_read_b128 v[176:179], v152 offset:1024
	ds_read_b128 v[180:183], v152 offset:2048
	ds_read_b128 v[184:187], v152 offset:3072
	s_add_u32 s26, s24, 0xfffc0080
	s_addc_u32 s27, s25, -1
	s_cmp_eq_u32 s50, 12
	s_cselect_b32 s29, s17, s27
	s_cselect_b32 s28, s41, s26
	s_cselect_b32 s27, s11, s45
	s_cselect_b32 s26, s42, s44
	s_add_u32 vcc_lo, s26, 0x80
	s_addc_u32 vcc_hi, s27, 0
	s_add_u32 s100, s28, 0x80
	s_addc_u32 s101, s29, 0
	s_add_i32 m0, s1, 0xc000
	ds_read_b128 v[194:197], v153
	ds_read_b128 v[198:201], v153 offset:1024
	ds_read_b128 v[202:205], v153 offset:2048
	ds_read_b128 v[206:209], v153 offset:3072
	ds_read_b128 v[210:213], v153 offset:4096
	ds_read_b128 v[214:217], v153 offset:5120
	ds_read_b128 v[218:221], v153 offset:6144
	global_load_lds_dwordx4 v138, s[24:25]
	s_add_i32 m0, s1, 0xe000
	ds_read_b128 v[222:225], v153 offset:7168
	global_load_lds_dwordx4 v140, s[24:25]
	s_waitcnt vmcnt(8)
	s_waitcnt lgkmcnt(0)
	s_barrier
; #define PG8_STAGE(bufoff, gbase, voff) do { _Pragma("unroll") for (int _i = 0; _i < 2; ++_i) \
;         __builtin_amdgcn_global_load_lds((const unsigned*)((const char*)(gbase) + (voff)[_i]), (PG8_LAS unsigned*)(lds + (bufoff) + ldsw + _i * 8192), 16, 0, 0); } while (0)
; #define PG8_LDA(dst, b, h) do { _Pragma("unroll") for (int m = 0; m < 4; ++m) _Pragma("unroll") for (int k = 0; k < 2; ++k) dst[m][k] = *(const PG8_LAS bf16x8*)(lds + PG8_SA(b, h) + aoff + m * 2048 + k * 1024); } while (0)
; #define PG8_MMA(ai, bj, At, Bt) do { __builtin_amdgcn_s_setprio(1); _Pragma("unroll") for (int m = 0; m < 4; ++m) _Pragma("unroll") for (int n = 0; n < 2; ++n) _Pragma("unroll") for (int k = 0; k < 2; ++k) \
;         acc[ai][bj][m][n] = __builtin_amdgcn_mfma_f32_16x16x32_bf16(Bt[n][k], At[m][k], acc[ai][bj][m][n], 0, 0, 0); __builtin_amdgcn_s_setprio(0); } while (0)
; #define PG8_WAIT_V(n) asm volatile("s_waitcnt vmcnt(" #n ")" ::: "memory")
; #define PG8_WAIT_L(n) asm volatile("s_waitcnt lgkmcnt(" #n ")" ::: "memory")
; #define PG8_BAR __builtin_amdgcn_s_barrier()
; #define PG8_SCHED __builtin_amdgcn_sched_barrier(0)
; template <class Epi, class Sched, bool ALIGN_EPI = false, bool SP2 = false>
; __device__ __forceinline__ void gemm_phase(PG8_LAS unsigned char* lds, const Gemm g, const Sched& S, const Epi& E) {
;     ...
;             PG8_WAIT_V(8); PG8_WAIT_L(0); PG8_BAR; PG8_MMA(0, 0, At, B0); PG8_MMA(0, 1, At, B1); PG8_BAR; PG8_SCHED;
;             PG8_LDA(At, 0, 1); PG8_STAGE(PG8_SB(0, 0), b2, voffB); PG8_STAGE(PG8_SB(0, 1), b2 + hstep, voffB); PG8_STAGE(PG8_SA(0, 0), a2, voffA);
;             PG8_WAIT_V(8); PG8_WAIT_L(0); PG8_BAR; PG8_MMA(1, 0, At, B0); PG8_MMA(1, 1, At, B1); PG8_BAR; PG8_SCHED;
	s_setprio 1
	s_waitcnt lgkmcnt(0)
	v_mfma_f32_16x16x32_bf16 v[124:127], v[156:159], v[194:197], v[124:127]
	v_mfma_f32_16x16x32_bf16 v[120:123], v[164:167], v[194:197], v[120:123]
	v_mfma_f32_16x16x32_bf16 v[108:111], v[156:159], v[202:205], v[108:111]
	v_mfma_f32_16x16x32_bf16 v[104:107], v[164:167], v[202:205], v[104:107]
	v_mfma_f32_16x16x32_bf16 v[92:95], v[156:159], v[210:213], v[92:95]
	v_mfma_f32_16x16x32_bf16 v[88:91], v[164:167], v[210:213], v[88:91]
	v_mfma_f32_16x16x32_bf16 v[76:79], v[156:159], v[218:221], v[76:79]
	v_mfma_f32_16x16x32_bf16 v[72:75], v[164:167], v[218:221], v[72:75]
	v_mfma_f32_16x16x32_bf16 v[124:127], v[160:163], v[198:201], v[124:127]
	v_mfma_f32_16x16x32_bf16 v[120:123], v[168:171], v[198:201], v[120:123]
	v_mfma_f32_16x16x32_bf16 v[108:111], v[160:163], v[206:209], v[108:111]
	v_mfma_f32_16x16x32_bf16 v[104:107], v[168:171], v[206:209], v[104:107]
	v_mfma_f32_16x16x32_bf16 v[92:95], v[160:163], v[214:217], v[92:95]
	v_mfma_f32_16x16x32_bf16 v[88:91], v[168:171], v[214:217], v[88:91]
	v_mfma_f32_16x16x32_bf16 v[76:79], v[160:163], v[222:225], v[76:79]
	v_mfma_f32_16x16x32_bf16 v[72:75], v[168:171], v[222:225], v[72:75]
	s_setprio 0
	s_setprio 1
	v_mfma_f32_16x16x32_bf16 v[116:119], v[172:175], v[194:197], v[116:119]
	v_mfma_f32_16x16x32_bf16 v[112:115], v[180:183], v[194:197], v[112:115]
	v_mfma_f32_16x16x32_bf16 v[100:103], v[172:175], v[202:205], v[100:103]
	v_mfma_f32_16x16x32_bf16 v[96:99], v[180:183], v[202:205], v[96:99]
	v_mfma_f32_16x16x32_bf16 v[84:87], v[172:175], v[210:213], v[84:87]
	v_mfma_f32_16x16x32_bf16 v[80:83], v[180:183], v[210:213], v[80:83]
	v_mfma_f32_16x16x32_bf16 v[68:71], v[172:175], v[218:221], v[68:71]
	v_mfma_f32_16x16x32_bf16 v[64:67], v[180:183], v[218:221], v[64:67]
	v_mfma_f32_16x16x32_bf16 v[116:119], v[176:179], v[198:201], v[116:119]
	v_mfma_f32_16x16x32_bf16 v[112:115], v[184:187], v[198:201], v[112:115]
	v_mfma_f32_16x16x32_bf16 v[100:103], v[176:179], v[206:209], v[100:103]
	v_mfma_f32_16x16x32_bf16 v[96:99], v[184:187], v[206:209], v[96:99]
	v_mfma_f32_16x16x32_bf16 v[84:87], v[176:179], v[214:217], v[84:87]
	v_mfma_f32_16x16x32_bf16 v[80:83], v[184:187], v[214:217], v[80:83]
	v_mfma_f32_16x16x32_bf16 v[68:71], v[176:179], v[222:225], v[68:71]
	v_mfma_f32_16x16x32_bf16 v[64:67], v[184:187], v[222:225], v[64:67]
	s_setprio 0
	s_barrier
	s_add_i32 s51, s38, s0
	s_mov_b32 m0, s51
	ds_read_b128 v[194:197], v153 offset:16384
	ds_read_b128 v[198:201], v153 offset:17408
	ds_read_b128 v[202:205], v153 offset:18432
	ds_read_b128 v[206:209], v153 offset:19456
	global_load_lds_dwordx4 v132, s[26:27]
	s_add_i32 m0, s51, 0x2000
	s_add_u32 s56, s26, 0x40000
	s_addc_u32 s57, s27, 0
	s_add_i32 s51, s39, s0
	global_load_lds_dwordx4 v128, s[26:27]
	s_mov_b32 m0, s51
	ds_read_b128 v[222:225], v153 offset:23552
	global_load_lds_dwordx4 v132, s[56:57]
	s_add_i32 m0, s51, 0x2000
	ds_read_b128 v[218:221], v153 offset:22528
	global_load_lds_dwordx4 v128, s[56:57]
	s_mov_b32 m0, s1
	ds_read_b128 v[214:217], v153 offset:21504
	global_load_lds_dwordx4 v134, s[28:29]
	s_mov_b32 m0, s23
	ds_read_b128 v[210:213], v153 offset:20480
	global_load_lds_dwordx4 v130, s[28:29]
	s_waitcnt vmcnt(8)
	s_waitcnt lgkmcnt(0)
	s_barrier
	s_setprio 1
	s_waitcnt lgkmcnt(0)
	v_mfma_f32_16x16x32_bf16 v[60:63], v[156:159], v[194:197], v[60:63]
	v_mfma_f32_16x16x32_bf16 v[56:59], v[164:167], v[194:197], v[56:59]
	v_mfma_f32_16x16x32_bf16 v[44:47], v[156:159], v[202:205], v[44:47]
	v_mfma_f32_16x16x32_bf16 v[40:43], v[164:167], v[202:205], v[40:43]
	v_mfma_f32_16x16x32_bf16 v[28:31], v[156:159], v[210:213], v[28:31]
	v_mfma_f32_16x16x32_bf16 v[24:27], v[164:167], v[210:213], v[24:27]
	v_mfma_f32_16x16x32_bf16 v[12:15], v[156:159], v[218:221], v[12:15]
	v_mfma_f32_16x16x32_bf16 v[8:11], v[164:167], v[218:221], v[8:11]
	v_mfma_f32_16x16x32_bf16 v[60:63], v[160:163], v[198:201], v[60:63]
	v_mfma_f32_16x16x32_bf16 v[56:59], v[168:171], v[198:201], v[56:59]
	v_mfma_f32_16x16x32_bf16 v[44:47], v[160:163], v[206:209], v[44:47]
	v_mfma_f32_16x16x32_bf16 v[40:43], v[168:171], v[206:209], v[40:43]
	v_mfma_f32_16x16x32_bf16 v[28:31], v[160:163], v[214:217], v[28:31]
	v_mfma_f32_16x16x32_bf16 v[24:27], v[168:171], v[214:217], v[24:27]
	v_mfma_f32_16x16x32_bf16 v[12:15], v[160:163], v[222:225], v[12:15]
	v_mfma_f32_16x16x32_bf16 v[8:11], v[168:171], v[222:225], v[8:11]
	s_setprio 0
	s_setprio 1
	v_mfma_f32_16x16x32_bf16 v[52:55], v[172:175], v[194:197], v[52:55]
	v_mfma_f32_16x16x32_bf16 v[48:51], v[180:183], v[194:197], v[48:51]
	v_mfma_f32_16x16x32_bf16 v[36:39], v[172:175], v[202:205], v[36:39]
	v_mfma_f32_16x16x32_bf16 v[32:35], v[180:183], v[202:205], v[32:35]
	v_mfma_f32_16x16x32_bf16 v[20:23], v[172:175], v[210:213], v[20:23]
	v_mfma_f32_16x16x32_bf16 v[16:19], v[180:183], v[210:213], v[16:19]
	v_mfma_f32_16x16x32_bf16 v[4:7], v[172:175], v[218:221], v[4:7]
	v_mfma_f32_16x16x32_bf16 v[0:3], v[180:183], v[218:221], v[0:3]
	v_mfma_f32_16x16x32_bf16 v[52:55], v[176:179], v[198:201], v[52:55]
	v_mfma_f32_16x16x32_bf16 v[48:51], v[184:187], v[198:201], v[48:51]
	v_mfma_f32_16x16x32_bf16 v[36:39], v[176:179], v[206:209], v[36:39]
	v_mfma_f32_16x16x32_bf16 v[32:35], v[184:187], v[206:209], v[32:35]
	v_mfma_f32_16x16x32_bf16 v[20:23], v[176:179], v[214:217], v[20:23]
	v_mfma_f32_16x16x32_bf16 v[16:19], v[184:187], v[214:217], v[16:19]
	v_mfma_f32_16x16x32_bf16 v[4:7], v[176:179], v[222:225], v[4:7]
	v_mfma_f32_16x16x32_bf16 v[0:3], v[184:187], v[222:225], v[0:3]
	s_setprio 0
	s_barrier
; #define PG8_STAGE(bufoff, gbase, voff) do { _Pragma("unroll") for (int _i = 0; _i < 2; ++_i) \
;         __builtin_amdgcn_global_load_lds((const unsigned*)((const char*)(gbase) + (voff)[_i]), (PG8_LAS unsigned*)(lds + (bufoff) + ldsw + _i * 8192), 16, 0, 0); } while (0)
; #define PG8_LDA(dst, b, h) do { _Pragma("unroll") for (int m = 0; m < 4; ++m) _Pragma("unroll") for (int k = 0; k < 2; ++k) dst[m][k] = *(const PG8_LAS bf16x8*)(lds + PG8_SA(b, h) + aoff + m * 2048 + k * 1024); } while (0)
; #define PG8_LDB(dst, b, h) do { _Pragma("unroll") for (int n = 0; n < 2; ++n) _Pragma("unroll") for (int k = 0; k < 2; ++k) dst[n][k] = *(const PG8_LAS bf16x8*)(lds + PG8_SB(b, h) + boff + n * 2048 + k * 1024); } while (0)
; template <class Epi, class Sched, bool ALIGN_EPI = false, bool SP2 = false>
; __device__ __forceinline__ void gemm_phase(PG8_LAS unsigned char* lds, const Gemm g, const Sched& S, const Epi& E) {
;     ...
;         for (int t = 0; t < nt; t += 2) {
;             const bool last = (t == nt - 2);
;             const char* a1 = cA + (size_t)(t + 1) * kstep;
;             const char* a2 = last ? nA : cA + (size_t)(t + 2) * kstep; const char* b2 = last ? nB : cB + (size_t)(t + 2) * kstep;
;             const char* a3 = a2 + kstep; const char* b3 = b2 + kstep;
;             if (last && has_next) S.a_ready(nxt);
;             if constexpr (SP2) {
;             PG8_LDB(B0, 0, 0); PG8_LDB(B1, 0, 1); PG8_SCHED; PG8_LDA(At, 0, 0); PG8_STAGE(PG8_SA(1, 1), a1 + hstep, voffA);
;             PG8_WAIT_V(8); PG8_WAIT_L(0); PG8_BAR; PG8_MMA(0, 0, At, B0); PG8_MMA(0, 1, At, B1); PG8_BAR; PG8_SCHED;
;             PG8_LDA(At, 0, 1); PG8_STAGE(PG8_SB(0, 0), b2, voffB); PG8_STAGE(PG8_SB(0, 1), b2 + hstep, voffB); PG8_STAGE(PG8_SA(0, 0), a2, voffA);
;             PG8_WAIT_V(8); PG8_WAIT_L(0); PG8_BAR; PG8_MMA(1, 0, At, B0); PG8_MMA(1, 1, At, B1); PG8_BAR; PG8_SCHED;
;             PG8_LDB(B0, 1, 0); PG8_LDB(B1, 1, 1); PG8_SCHED; PG8_LDA(At, 1, 0); PG8_STAGE(PG8_SA(0, 1), a2 + hstep, voffA);
;             PG8_WAIT_V(8); PG8_WAIT_L(0); PG8_BAR; PG8_MMA(0, 0, At, B0); PG8_MMA(0, 1, At, B1); PG8_BAR; PG8_SCHED;
;             PG8_LDA(At, 1, 1); PG8_STAGE(PG8_SB(1, 0), b3, voffB); PG8_STAGE(PG8_SB(1, 1), b3 + hstep, voffB); PG8_STAGE(PG8_SA(1, 0), a3, voffA);
;             PG8_WAIT_V(8); PG8_WAIT_L(0); PG8_BAR; PG8_MMA(1, 0, At, B0); PG8_MMA(1, 1, At, B1); PG8_BAR; PG8_SCHED;
	s_add_i32 s51, 0, 0x18000
	s_add_i32 s56, 0, 0x1c000
	ds_read_b128 v[156:159], v240
	ds_read_b128 v[160:163], v240 offset:1024
	ds_read_b128 v[164:167], v240 offset:2048
	ds_read_b128 v[168:171], v240 offset:3072
	ds_read_b128 v[172:175], v241
	ds_read_b128 v[176:179], v241 offset:1024
	ds_read_b128 v[180:183], v241 offset:2048
	ds_read_b128 v[184:187], v241 offset:3072
	s_add_u32 s28, s28, 0x40000
	s_addc_u32 s29, s29, 0
	s_mov_b32 m0, s31
	ds_read_b128 v[194:197], v153 offset:32768
	ds_read_b128 v[198:201], v153 offset:33792
	ds_read_b128 v[202:205], v153 offset:34816
	ds_read_b128 v[206:209], v153 offset:35840
	ds_read_b128 v[210:213], v153 offset:36864
	ds_read_b128 v[214:217], v153 offset:37888
	ds_read_b128 v[218:221], v153 offset:38912
	global_load_lds_dwordx4 v134, s[28:29]
	s_mov_b32 m0, s34
	ds_read_b128 v[222:225], v153 offset:39936
	global_load_lds_dwordx4 v130, s[28:29]
	s_waitcnt vmcnt(8)
	s_waitcnt lgkmcnt(0)
	s_barrier
	s_setprio 1
	s_waitcnt lgkmcnt(0)
	v_mfma_f32_16x16x32_bf16 v[124:127], v[156:159], v[194:197], v[124:127]
	v_mfma_f32_16x16x32_bf16 v[120:123], v[164:167], v[194:197], v[120:123]
	v_mfma_f32_16x16x32_bf16 v[108:111], v[156:159], v[202:205], v[108:111]
	v_mfma_f32_16x16x32_bf16 v[104:107], v[164:167], v[202:205], v[104:107]
	v_mfma_f32_16x16x32_bf16 v[92:95], v[156:159], v[210:213], v[92:95]
	v_mfma_f32_16x16x32_bf16 v[88:91], v[164:167], v[210:213], v[88:91]
	v_mfma_f32_16x16x32_bf16 v[76:79], v[156:159], v[218:221], v[76:79]
	v_mfma_f32_16x16x32_bf16 v[72:75], v[164:167], v[218:221], v[72:75]
	v_mfma_f32_16x16x32_bf16 v[124:127], v[160:163], v[198:201], v[124:127]
	v_mfma_f32_16x16x32_bf16 v[120:123], v[168:171], v[198:201], v[120:123]
	v_mfma_f32_16x16x32_bf16 v[108:111], v[160:163], v[206:209], v[108:111]
	v_mfma_f32_16x16x32_bf16 v[104:107], v[168:171], v[206:209], v[104:107]
	v_mfma_f32_16x16x32_bf16 v[92:95], v[160:163], v[214:217], v[92:95]
	v_mfma_f32_16x16x32_bf16 v[88:91], v[168:171], v[214:217], v[88:91]
	v_mfma_f32_16x16x32_bf16 v[76:79], v[160:163], v[222:225], v[76:79]
	v_mfma_f32_16x16x32_bf16 v[72:75], v[168:171], v[222:225], v[72:75]
	s_setprio 0
	s_setprio 1
	v_mfma_f32_16x16x32_bf16 v[116:119], v[172:175], v[194:197], v[116:119]
	v_mfma_f32_16x16x32_bf16 v[112:115], v[180:183], v[194:197], v[112:115]
	v_mfma_f32_16x16x32_bf16 v[100:103], v[172:175], v[202:205], v[100:103]
	v_mfma_f32_16x16x32_bf16 v[96:99], v[180:183], v[202:205], v[96:99]
	v_mfma_f32_16x16x32_bf16 v[84:87], v[172:175], v[210:213], v[84:87]
	v_mfma_f32_16x16x32_bf16 v[80:83], v[180:183], v[210:213], v[80:83]
	v_mfma_f32_16x16x32_bf16 v[68:71], v[172:175], v[218:221], v[68:71]
	v_mfma_f32_16x16x32_bf16 v[64:67], v[180:183], v[218:221], v[64:67]
	v_mfma_f32_16x16x32_bf16 v[116:119], v[176:179], v[198:201], v[116:119]
	v_mfma_f32_16x16x32_bf16 v[112:115], v[184:187], v[198:201], v[112:115]
	v_mfma_f32_16x16x32_bf16 v[100:103], v[176:179], v[206:209], v[100:103]
	v_mfma_f32_16x16x32_bf16 v[96:99], v[184:187], v[206:209], v[96:99]
	v_mfma_f32_16x16x32_bf16 v[84:87], v[176:179], v[214:217], v[84:87]
	v_mfma_f32_16x16x32_bf16 v[80:83], v[184:187], v[214:217], v[80:83]
	v_mfma_f32_16x16x32_bf16 v[68:71], v[176:179], v[222:225], v[68:71]
	v_mfma_f32_16x16x32_bf16 v[64:67], v[184:187], v[222:225], v[64:67]
	s_setprio 0
	s_barrier
	s_add_i32 s28, s51, s0
	s_mov_b32 m0, s28
	ds_read_b128 v[194:197], v153 offset:49152
	ds_read_b128 v[198:201], v153 offset:50176
	ds_read_b128 v[202:205], v153 offset:51200
	ds_read_b128 v[206:209], v153 offset:52224
	global_load_lds_dwordx4 v132, vcc
	s_add_i32 m0, s28, 0x2000
	s_add_u32 s26, s26, 0x40080
	s_addc_u32 s27, s27, 0
	s_add_i32 s28, s56, s0
	global_load_lds_dwordx4 v128, vcc
	s_mov_b32 m0, s28
	ds_read_b128 v[222:225], v153 offset:56320
	global_load_lds_dwordx4 v132, s[26:27]
	s_add_i32 m0, s28, 0x2000
	ds_read_b128 v[218:221], v153 offset:55296
	global_load_lds_dwordx4 v128, s[26:27]
	s_mov_b32 m0, s36
	ds_read_b128 v[214:217], v153 offset:54272
	global_load_lds_dwordx4 v134, s[100:101]
	s_mov_b32 m0, s37
	ds_read_b128 v[210:213], v153 offset:53248
	global_load_lds_dwordx4 v130, s[100:101]
	s_waitcnt vmcnt(8)
	s_waitcnt lgkmcnt(0)
	s_barrier
	s_setprio 1
	s_waitcnt lgkmcnt(0)
	v_mfma_f32_16x16x32_bf16 v[60:63], v[156:159], v[194:197], v[60:63]
	v_mfma_f32_16x16x32_bf16 v[56:59], v[164:167], v[194:197], v[56:59]
	v_mfma_f32_16x16x32_bf16 v[44:47], v[156:159], v[202:205], v[44:47]
	v_mfma_f32_16x16x32_bf16 v[40:43], v[164:167], v[202:205], v[40:43]
	v_mfma_f32_16x16x32_bf16 v[28:31], v[156:159], v[210:213], v[28:31]
	v_mfma_f32_16x16x32_bf16 v[24:27], v[164:167], v[210:213], v[24:27]
	v_mfma_f32_16x16x32_bf16 v[12:15], v[156:159], v[218:221], v[12:15]
	v_mfma_f32_16x16x32_bf16 v[8:11], v[164:167], v[218:221], v[8:11]
	v_mfma_f32_16x16x32_bf16 v[60:63], v[160:163], v[198:201], v[60:63]
	v_mfma_f32_16x16x32_bf16 v[56:59], v[168:171], v[198:201], v[56:59]
	v_mfma_f32_16x16x32_bf16 v[44:47], v[160:163], v[206:209], v[44:47]
	v_mfma_f32_16x16x32_bf16 v[40:43], v[168:171], v[206:209], v[40:43]
	v_mfma_f32_16x16x32_bf16 v[28:31], v[160:163], v[214:217], v[28:31]
	v_mfma_f32_16x16x32_bf16 v[24:27], v[168:171], v[214:217], v[24:27]
	v_mfma_f32_16x16x32_bf16 v[12:15], v[160:163], v[222:225], v[12:15]
	v_mfma_f32_16x16x32_bf16 v[8:11], v[168:171], v[222:225], v[8:11]
	s_setprio 0
	s_setprio 1
	v_mfma_f32_16x16x32_bf16 v[52:55], v[172:175], v[194:197], v[52:55]
	v_mfma_f32_16x16x32_bf16 v[48:51], v[180:183], v[194:197], v[48:51]
	v_mfma_f32_16x16x32_bf16 v[36:39], v[172:175], v[202:205], v[36:39]
	v_mfma_f32_16x16x32_bf16 v[32:35], v[180:183], v[202:205], v[32:35]
	v_mfma_f32_16x16x32_bf16 v[20:23], v[172:175], v[210:213], v[20:23]
	v_mfma_f32_16x16x32_bf16 v[16:19], v[180:183], v[210:213], v[16:19]
	v_mfma_f32_16x16x32_bf16 v[4:7], v[172:175], v[218:221], v[4:7]
	v_mfma_f32_16x16x32_bf16 v[0:3], v[180:183], v[218:221], v[0:3]
	v_mfma_f32_16x16x32_bf16 v[52:55], v[176:179], v[198:201], v[52:55]
	v_mfma_f32_16x16x32_bf16 v[48:51], v[184:187], v[198:201], v[48:51]
	v_mfma_f32_16x16x32_bf16 v[36:39], v[176:179], v[206:209], v[36:39]
	v_mfma_f32_16x16x32_bf16 v[32:35], v[184:187], v[206:209], v[32:35]
	v_mfma_f32_16x16x32_bf16 v[20:23], v[176:179], v[214:217], v[20:23]
	v_mfma_f32_16x16x32_bf16 v[16:19], v[184:187], v[214:217], v[16:19]
	v_mfma_f32_16x16x32_bf16 v[4:7], v[176:179], v[222:225], v[4:7]
	v_mfma_f32_16x16x32_bf16 v[0:3], v[184:187], v[222:225], v[0:3]
	s_setprio 0
	s_barrier
	s_add_i32 s50, s50, 2
	s_add_u32 s24, s24, 0x100
	s_addc_u32 s25, s25, 0
	s_add_u32 s44, s44, 0x100
	s_addc_u32 s45, s45, 0
	s_cmp_gt_u32 s50, 13
	s_cbranch_scc0 .LBB0_462
	s_and_b64 vcc, exec, s[14:15]
	s_cbranch_vccz .LBB0_465
	s_barrier

; #define PG8_STAGE(bufoff, gbase, voff) do { _Pragma("unroll") for (int _i = 0; _i < 2; ++_i) \
;         __builtin_amdgcn_global_load_lds((const unsigned*)((const char*)(gbase) + (voff)[_i]), (PG8_LAS unsigned*)(lds + (bufoff) + ldsw + _i * 8192), 16, 0, 0); } while (0)
; #define PG8_LDA(dst, b, h) do { _Pragma("unroll") for (int m = 0; m < 4; ++m) _Pragma("unroll") for (int k = 0; k < 2; ++k) dst[m][k] = *(const PG8_LAS bf16x8*)(lds + PG8_SA(b, h) + aoff + m * 2048 + k * 1024); } while (0)
; #define PG8_LDB(dst, b, h) do { _Pragma("unroll") for (int n = 0; n < 2; ++n) _Pragma("unroll") for (int k = 0; k < 2; ++k) dst[n][k] = *(const PG8_LAS bf16x8*)(lds + PG8_SB(b, h) + boff + n * 2048 + k * 1024); } while (0)
; #define PG8_WAIT_V(n) asm volatile("s_waitcnt vmcnt(" #n ")" ::: "memory")
; #define PG8_WAIT_L(n) asm volatile("s_waitcnt lgkmcnt(" #n ")" ::: "memory")
; #define PG8_BAR __builtin_amdgcn_s_barrier()
; template <class Epi, class Sched, bool ALIGN_EPI = false, bool SP2 = false>
; __device__ __forceinline__ void gemm_phase(PG8_LAS unsigned char* lds, const Gemm g, const Sched& S, const Epi& E) {
;     ...
;         const bool has_next = S.next(ui + 1, nxt);
;         const char* nA = has_next ? (const char*)g.A + (size_t)nxt.pm * tstep + (size_t)nxt.pn * g.a_pn_off : cA; const char* nB = has_next ? (const char*)g.Bt + (size_t)nxt.pn * tstep : cB;
;         for (int t = 0; t < nt; t += 2) {
;             const bool last = (t == nt - 2);
;             const char* a1 = cA + (size_t)(t + 1) * kstep;
;             const char* a2 = last ? nA : cA + (size_t)(t + 2) * kstep; const char* b2 = last ? nB : cB + (size_t)(t + 2) * kstep;
;             const char* a3 = a2 + kstep; const char* b3 = b2 + kstep;
;             if (last && has_next) S.a_ready(nxt);
;             if constexpr (SP2) {
;             PG8_LDB(B0, 0, 0); PG8_LDB(B1, 0, 1); PG8_SCHED; PG8_LDA(At, 0, 0); PG8_STAGE(PG8_SA(1, 1), a1 + hstep, voffA);
;             PG8_WAIT_V(8); PG8_WAIT_L(0); PG8_BAR; PG8_MMA(0, 0, At, B0); PG8_MMA(0, 1, At, B1); PG8_BAR; PG8_SCHED;
;     ...
; #pragma unroll
;         for (int a = 0; a < 2; ++a)
; #pragma unroll
;             for (int b = 0; b < 2; ++b)
; #pragma unroll
;                 for (int m = 0; m < 4; ++m)
; #pragma unroll
;                     for (int n = 0; n < 2; ++n) acc[a][b][m][n] = (f32x4){0.f, 0.f, 0.f, 0.f};
;         cur = nxt; cA = nA; cB = nB; ++ui;
.LBB0_500:
	s_ashr_i32 s19, s18, 31
	s_lshl_b64 s[20:21], s[18:19], 21
	s_add_u32 s20, s48, s20
	s_addc_u32 s21, s49, s21
	s_and_b64 s[22:23], s[4:5], exec
	s_cselect_b32 s19, s21, s27
	s_cselect_b32 s25, s20, s26
	s_ashr_i32 s17, s16, 31
	s_lshl_b64 s[22:23], s[16:17], 21
	s_add_u32 s22, s76, s22
	s_addc_u32 s23, s77, s23
	s_and_b64 s[34:35], s[4:5], exec
	s_cselect_b32 s17, s23, s29
	s_cselect_b32 s45, s22, s28
	s_add_u32 s26, s26, 0x100080
	s_addc_u32 s27, s27, 0
	s_add_u32 s50, s28, 0x100
	v_mov_b32_e32 v0, 0
	s_addc_u32 s51, s29, 0
	s_mov_b32 s56, -2
	v_mov_b32_e32 v1, v0
	v_mov_b32_e32 v2, v0
	v_mov_b32_e32 v3, v0
	v_mov_b32_e32 v4, v0
	v_mov_b32_e32 v5, v0
	v_mov_b32_e32 v6, v0
	v_mov_b32_e32 v7, v0
	v_mov_b32_e32 v16, v0
	v_mov_b32_e32 v17, v0
	v_mov_b32_e32 v18, v0
	v_mov_b32_e32 v19, v0
	v_mov_b32_e32 v20, v0
	v_mov_b32_e32 v21, v0
	v_mov_b32_e32 v22, v0
	v_mov_b32_e32 v23, v0
	v_mov_b32_e32 v32, v0
	v_mov_b32_e32 v33, v0
	v_mov_b32_e32 v34, v0
	v_mov_b32_e32 v35, v0
	v_mov_b32_e32 v36, v0
	v_mov_b32_e32 v37, v0
	v_mov_b32_e32 v38, v0
	v_mov_b32_e32 v39, v0
	v_mov_b32_e32 v48, v0
	v_mov_b32_e32 v49, v0
	v_mov_b32_e32 v50, v0
	v_mov_b32_e32 v51, v0
	v_mov_b32_e32 v52, v0
	v_mov_b32_e32 v53, v0
	v_mov_b32_e32 v54, v0
	v_mov_b32_e32 v55, v0
	v_mov_b32_e32 v8, v0
	v_mov_b32_e32 v9, v0
	v_mov_b32_e32 v10, v0
	v_mov_b32_e32 v11, v0
	v_mov_b32_e32 v12, v0
	v_mov_b32_e32 v13, v0
	v_mov_b32_e32 v14, v0
	v_mov_b32_e32 v15, v0
	v_mov_b32_e32 v24, v0
	v_mov_b32_e32 v25, v0
	v_mov_b32_e32 v26, v0
	v_mov_b32_e32 v27, v0
	v_mov_b32_e32 v28, v0
	v_mov_b32_e32 v29, v0
	v_mov_b32_e32 v30, v0
	v_mov_b32_e32 v31, v0
	v_mov_b32_e32 v40, v0
	v_mov_b32_e32 v41, v0
	v_mov_b32_e32 v42, v0
	v_mov_b32_e32 v43, v0
	v_mov_b32_e32 v44, v0
	v_mov_b32_e32 v45, v0
	v_mov_b32_e32 v46, v0
	v_mov_b32_e32 v47, v0
	v_mov_b32_e32 v56, v0
	v_mov_b32_e32 v57, v0
	v_mov_b32_e32 v58, v0
	v_mov_b32_e32 v59, v0
	v_mov_b32_e32 v60, v0
	v_mov_b32_e32 v61, v0
	v_mov_b32_e32 v62, v0
	v_mov_b32_e32 v63, v0
	v_mov_b32_e32 v64, v0
	v_mov_b32_e32 v65, v0
	v_mov_b32_e32 v66, v0
	v_mov_b32_e32 v67, v0
	v_mov_b32_e32 v68, v0
	v_mov_b32_e32 v69, v0
	v_mov_b32_e32 v70, v0
	v_mov_b32_e32 v71, v0
	v_mov_b32_e32 v80, v0
	v_mov_b32_e32 v81, v0
	v_mov_b32_e32 v82, v0
	v_mov_b32_e32 v83, v0
	v_mov_b32_e32 v84, v0
	v_mov_b32_e32 v85, v0
	v_mov_b32_e32 v86, v0
	v_mov_b32_e32 v87, v0
	v_mov_b32_e32 v96, v0
	v_mov_b32_e32 v97, v0
	v_mov_b32_e32 v98, v0
	v_mov_b32_e32 v99, v0
	v_mov_b32_e32 v100, v0
	v_mov_b32_e32 v101, v0
	v_mov_b32_e32 v102, v0
	v_mov_b32_e32 v103, v0
	v_mov_b32_e32 v112, v0
	v_mov_b32_e32 v113, v0
	v_mov_b32_e32 v114, v0
	v_mov_b32_e32 v115, v0
	v_mov_b32_e32 v116, v0
	v_mov_b32_e32 v117, v0
	v_mov_b32_e32 v118, v0
	v_mov_b32_e32 v119, v0
	v_mov_b32_e32 v72, v0
	v_mov_b32_e32 v73, v0
	v_mov_b32_e32 v74, v0
	v_mov_b32_e32 v75, v0
	v_mov_b32_e32 v76, v0
	v_mov_b32_e32 v77, v0
	v_mov_b32_e32 v78, v0
	v_mov_b32_e32 v79, v0
	v_mov_b32_e32 v88, v0
	v_mov_b32_e32 v89, v0
	v_mov_b32_e32 v90, v0
	v_mov_b32_e32 v91, v0
	v_mov_b32_e32 v92, v0
	v_mov_b32_e32 v93, v0
	v_mov_b32_e32 v94, v0
	v_mov_b32_e32 v95, v0
	v_mov_b32_e32 v104, v0
	v_mov_b32_e32 v105, v0
	v_mov_b32_e32 v106, v0
	v_mov_b32_e32 v107, v0
	v_mov_b32_e32 v108, v0
	v_mov_b32_e32 v109, v0
	v_mov_b32_e32 v110, v0
	v_mov_b32_e32 v111, v0
	v_mov_b32_e32 v120, v0
	v_mov_b32_e32 v121, v0
	v_mov_b32_e32 v122, v0
	v_mov_b32_e32 v123, v0
	v_mov_b32_e32 v124, v0
	v_mov_b32_e32 v125, v0
	v_mov_b32_e32 v126, v0
	v_mov_b32_e32 v127, v0
	v_add_u32_e32 v240, 0x18000, v149
	v_add_u32_e32 v241, 0x1c000, v149
.LBB0_501:
	ds_read_b128 v[144:147], v151
	ds_read_b128 v[154:157], v151 offset:1024
	ds_read_b128 v[158:161], v151 offset:2048
	ds_read_b128 v[162:165], v151 offset:3072
	ds_read_b128 v[166:169], v152
	ds_read_b128 v[170:173], v152 offset:1024
	ds_read_b128 v[174:177], v152 offset:2048
	ds_read_b128 v[178:181], v152 offset:3072
	s_add_u32 s28, s26, 0xfff00080
	s_addc_u32 s29, s27, -1
	s_cmp_eq_u32 s56, 60
	s_cselect_b32 s35, s19, s29
	s_cselect_b32 s34, s25, s28
	s_cselect_b32 s29, s17, s51
	s_cselect_b32 s28, s45, s50
	s_add_u32 vcc_lo, s28, 0x80
	s_addc_u32 vcc_hi, s29, 0
	s_add_u32 s100, s34, 0x80
	s_addc_u32 s101, s35, 0
	s_add_i32 m0, s1, 0xc000
	ds_read_b128 v[182:185], v153
	ds_read_b128 v[186:189], v153 offset:1024
	ds_read_b128 v[194:197], v153 offset:2048
	ds_read_b128 v[198:201], v153 offset:3072
	ds_read_b128 v[202:205], v153 offset:4096
	ds_read_b128 v[206:209], v153 offset:5120
	ds_read_b128 v[210:213], v153 offset:6144
	global_load_lds_dwordx4 v136, s[26:27]
	s_add_i32 m0, s1, 0xe000
	ds_read_b128 v[214:217], v153 offset:7168
	global_load_lds_dwordx4 v138, s[26:27]
	s_waitcnt vmcnt(8)
	s_waitcnt lgkmcnt(0)
	s_barrier
; #define PG8_STAGE(bufoff, gbase, voff) do { _Pragma("unroll") for (int _i = 0; _i < 2; ++_i) \
;         __builtin_amdgcn_global_load_lds((const unsigned*)((const char*)(gbase) + (voff)[_i]), (PG8_LAS unsigned*)(lds + (bufoff) + ldsw + _i * 8192), 16, 0, 0); } while (0)
; #define PG8_LDA(dst, b, h) do { _Pragma("unroll") for (int m = 0; m < 4; ++m) _Pragma("unroll") for (int k = 0; k < 2; ++k) dst[m][k] = *(const PG8_LAS bf16x8*)(lds + PG8_SA(b, h) + aoff + m * 2048 + k * 1024); } while (0)
; #define PG8_MMA(ai, bj, At, Bt) do { __builtin_amdgcn_s_setprio(1); _Pragma("unroll") for (int m = 0; m < 4; ++m) _Pragma("unroll") for (int n = 0; n < 2; ++n) _Pragma("unroll") for (int k = 0; k < 2; ++k) \
;         acc[ai][bj][m][n] = __builtin_amdgcn_mfma_f32_16x16x32_bf16(Bt[n][k], At[m][k], acc[ai][bj][m][n], 0, 0, 0); __builtin_amdgcn_s_setprio(0); } while (0)
; #define PG8_WAIT_V(n) asm volatile("s_waitcnt vmcnt(" #n ")" ::: "memory")
; #define PG8_WAIT_L(n) asm volatile("s_waitcnt lgkmcnt(" #n ")" ::: "memory")
; #define PG8_BAR __builtin_amdgcn_s_barrier()
; #define PG8_SCHED __builtin_amdgcn_sched_barrier(0)
; template <class Epi, class Sched, bool ALIGN_EPI = false, bool SP2 = false>
; __device__ __forceinline__ void gemm_phase(PG8_LAS unsigned char* lds, const Gemm g, const Sched& S, const Epi& E) {
;     ...
;             PG8_WAIT_V(8); PG8_WAIT_L(0); PG8_BAR; PG8_MMA(0, 0, At, B0); PG8_MMA(0, 1, At, B1); PG8_BAR; PG8_SCHED;
;             PG8_LDA(At, 0, 1); PG8_STAGE(PG8_SB(0, 0), b2, voffB); PG8_STAGE(PG8_SB(0, 1), b2 + hstep, voffB); PG8_STAGE(PG8_SA(0, 0), a2, voffA);
;             PG8_WAIT_V(8); PG8_WAIT_L(0); PG8_BAR; PG8_MMA(1, 0, At, B0); PG8_MMA(1, 1, At, B1); PG8_BAR; PG8_SCHED;
	s_setprio 1
	s_waitcnt lgkmcnt(0)
	v_mfma_f32_16x16x32_bf16 v[124:127], v[144:147], v[182:185], v[124:127]
	v_mfma_f32_16x16x32_bf16 v[120:123], v[158:161], v[182:185], v[120:123]
	v_mfma_f32_16x16x32_bf16 v[108:111], v[144:147], v[194:197], v[108:111]
	v_mfma_f32_16x16x32_bf16 v[104:107], v[158:161], v[194:197], v[104:107]
	v_mfma_f32_16x16x32_bf16 v[92:95], v[144:147], v[202:205], v[92:95]
	v_mfma_f32_16x16x32_bf16 v[88:91], v[158:161], v[202:205], v[88:91]
	v_mfma_f32_16x16x32_bf16 v[76:79], v[144:147], v[210:213], v[76:79]
	v_mfma_f32_16x16x32_bf16 v[72:75], v[158:161], v[210:213], v[72:75]
	v_mfma_f32_16x16x32_bf16 v[124:127], v[154:157], v[186:189], v[124:127]
	v_mfma_f32_16x16x32_bf16 v[120:123], v[162:165], v[186:189], v[120:123]
	v_mfma_f32_16x16x32_bf16 v[108:111], v[154:157], v[198:201], v[108:111]
	v_mfma_f32_16x16x32_bf16 v[104:107], v[162:165], v[198:201], v[104:107]
	v_mfma_f32_16x16x32_bf16 v[92:95], v[154:157], v[206:209], v[92:95]
	v_mfma_f32_16x16x32_bf16 v[88:91], v[162:165], v[206:209], v[88:91]
	v_mfma_f32_16x16x32_bf16 v[76:79], v[154:157], v[214:217], v[76:79]
	v_mfma_f32_16x16x32_bf16 v[72:75], v[162:165], v[214:217], v[72:75]
	s_setprio 0
	s_setprio 1
	v_mfma_f32_16x16x32_bf16 v[116:119], v[166:169], v[182:185], v[116:119]
	v_mfma_f32_16x16x32_bf16 v[112:115], v[174:177], v[182:185], v[112:115]
	v_mfma_f32_16x16x32_bf16 v[100:103], v[166:169], v[194:197], v[100:103]
	v_mfma_f32_16x16x32_bf16 v[96:99], v[174:177], v[194:197], v[96:99]
	v_mfma_f32_16x16x32_bf16 v[84:87], v[166:169], v[202:205], v[84:87]
	v_mfma_f32_16x16x32_bf16 v[80:83], v[174:177], v[202:205], v[80:83]
	v_mfma_f32_16x16x32_bf16 v[68:71], v[166:169], v[210:213], v[68:71]
	v_mfma_f32_16x16x32_bf16 v[64:67], v[174:177], v[210:213], v[64:67]
	v_mfma_f32_16x16x32_bf16 v[116:119], v[170:173], v[186:189], v[116:119]
	v_mfma_f32_16x16x32_bf16 v[112:115], v[178:181], v[186:189], v[112:115]
	v_mfma_f32_16x16x32_bf16 v[100:103], v[170:173], v[198:201], v[100:103]
	v_mfma_f32_16x16x32_bf16 v[96:99], v[178:181], v[198:201], v[96:99]
	v_mfma_f32_16x16x32_bf16 v[84:87], v[170:173], v[206:209], v[84:87]
	v_mfma_f32_16x16x32_bf16 v[80:83], v[178:181], v[206:209], v[80:83]
	v_mfma_f32_16x16x32_bf16 v[68:71], v[170:173], v[214:217], v[68:71]
	v_mfma_f32_16x16x32_bf16 v[64:67], v[178:181], v[214:217], v[64:67]
	s_setprio 0
	s_barrier
	s_add_i32 s57, s41, s0
	s_mov_b32 m0, s57
	ds_read_b128 v[182:185], v153 offset:16384
	ds_read_b128 v[186:189], v153 offset:17408
	ds_read_b128 v[194:197], v153 offset:18432
	ds_read_b128 v[198:201], v153 offset:19456
	global_load_lds_dwordx4 v130, s[28:29]
	s_add_i32 m0, s57, 0x2000
	s_add_u32 s58, s28, 0x100000
	s_addc_u32 s59, s29, 0
	s_add_i32 s57, s42, s0
	global_load_lds_dwordx4 v134, s[28:29]
	s_mov_b32 m0, s57
	ds_read_b128 v[214:217], v153 offset:23552
	global_load_lds_dwordx4 v130, s[58:59]
	s_add_i32 m0, s57, 0x2000
	ds_read_b128 v[210:213], v153 offset:22528
	global_load_lds_dwordx4 v134, s[58:59]
	s_mov_b32 m0, s1
	ds_read_b128 v[206:209], v153 offset:21504
	global_load_lds_dwordx4 v128, s[34:35]
	s_mov_b32 m0, s31
	ds_read_b128 v[202:205], v153 offset:20480
	global_load_lds_dwordx4 v132, s[34:35]
	s_waitcnt vmcnt(8)
	s_waitcnt lgkmcnt(0)
	s_barrier
	s_setprio 1
	s_waitcnt lgkmcnt(0)
	v_mfma_f32_16x16x32_bf16 v[60:63], v[144:147], v[182:185], v[60:63]
	v_mfma_f32_16x16x32_bf16 v[56:59], v[158:161], v[182:185], v[56:59]
	v_mfma_f32_16x16x32_bf16 v[44:47], v[144:147], v[194:197], v[44:47]
	v_mfma_f32_16x16x32_bf16 v[40:43], v[158:161], v[194:197], v[40:43]
	v_mfma_f32_16x16x32_bf16 v[28:31], v[144:147], v[202:205], v[28:31]
	v_mfma_f32_16x16x32_bf16 v[24:27], v[158:161], v[202:205], v[24:27]
	v_mfma_f32_16x16x32_bf16 v[12:15], v[144:147], v[210:213], v[12:15]
	v_mfma_f32_16x16x32_bf16 v[8:11], v[158:161], v[210:213], v[8:11]
	v_mfma_f32_16x16x32_bf16 v[60:63], v[154:157], v[186:189], v[60:63]
	v_mfma_f32_16x16x32_bf16 v[56:59], v[162:165], v[186:189], v[56:59]
	v_mfma_f32_16x16x32_bf16 v[44:47], v[154:157], v[198:201], v[44:47]
	v_mfma_f32_16x16x32_bf16 v[40:43], v[162:165], v[198:201], v[40:43]
	v_mfma_f32_16x16x32_bf16 v[28:31], v[154:157], v[206:209], v[28:31]
	v_mfma_f32_16x16x32_bf16 v[24:27], v[162:165], v[206:209], v[24:27]
	v_mfma_f32_16x16x32_bf16 v[12:15], v[154:157], v[214:217], v[12:15]
	v_mfma_f32_16x16x32_bf16 v[8:11], v[162:165], v[214:217], v[8:11]
	s_setprio 0
	s_setprio 1
	v_mfma_f32_16x16x32_bf16 v[52:55], v[166:169], v[182:185], v[52:55]
	v_mfma_f32_16x16x32_bf16 v[48:51], v[174:177], v[182:185], v[48:51]
	v_mfma_f32_16x16x32_bf16 v[36:39], v[166:169], v[194:197], v[36:39]
	v_mfma_f32_16x16x32_bf16 v[32:35], v[174:177], v[194:197], v[32:35]
	v_mfma_f32_16x16x32_bf16 v[20:23], v[166:169], v[202:205], v[20:23]
	v_mfma_f32_16x16x32_bf16 v[16:19], v[174:177], v[202:205], v[16:19]
	v_mfma_f32_16x16x32_bf16 v[4:7], v[166:169], v[210:213], v[4:7]
	v_mfma_f32_16x16x32_bf16 v[0:3], v[174:177], v[210:213], v[0:3]
	v_mfma_f32_16x16x32_bf16 v[52:55], v[170:173], v[186:189], v[52:55]
	v_mfma_f32_16x16x32_bf16 v[48:51], v[178:181], v[186:189], v[48:51]
	v_mfma_f32_16x16x32_bf16 v[36:39], v[170:173], v[198:201], v[36:39]
	v_mfma_f32_16x16x32_bf16 v[32:35], v[178:181], v[198:201], v[32:35]
	v_mfma_f32_16x16x32_bf16 v[20:23], v[170:173], v[206:209], v[20:23]
	v_mfma_f32_16x16x32_bf16 v[16:19], v[178:181], v[206:209], v[16:19]
	v_mfma_f32_16x16x32_bf16 v[4:7], v[170:173], v[214:217], v[4:7]
	v_mfma_f32_16x16x32_bf16 v[0:3], v[178:181], v[214:217], v[0:3]
	s_setprio 0
	s_barrier
; #define PG8_STAGE(bufoff, gbase, voff) do { _Pragma("unroll") for (int _i = 0; _i < 2; ++_i) \
;         __builtin_amdgcn_global_load_lds((const unsigned*)((const char*)(gbase) + (voff)[_i]), (PG8_LAS unsigned*)(lds + (bufoff) + ldsw + _i * 8192), 16, 0, 0); } while (0)
; #define PG8_LDA(dst, b, h) do { _Pragma("unroll") for (int m = 0; m < 4; ++m) _Pragma("unroll") for (int k = 0; k < 2; ++k) dst[m][k] = *(const PG8_LAS bf16x8*)(lds + PG8_SA(b, h) + aoff + m * 2048 + k * 1024); } while (0)
; #define PG8_LDB(dst, b, h) do { _Pragma("unroll") for (int n = 0; n < 2; ++n) _Pragma("unroll") for (int k = 0; k < 2; ++k) dst[n][k] = *(const PG8_LAS bf16x8*)(lds + PG8_SB(b, h) + boff + n * 2048 + k * 1024); } while (0)
; template <class Epi, class Sched, bool ALIGN_EPI = false, bool SP2 = false>
; __device__ __forceinline__ void gemm_phase(PG8_LAS unsigned char* lds, const Gemm g, const Sched& S, const Epi& E) {
;     ...
;         for (int t = 0; t < nt; t += 2) {
;             const bool last = (t == nt - 2);
;             const char* a1 = cA + (size_t)(t + 1) * kstep;
;             const char* a2 = last ? nA : cA + (size_t)(t + 2) * kstep; const char* b2 = last ? nB : cB + (size_t)(t + 2) * kstep;
;             const char* a3 = a2 + kstep; const char* b3 = b2 + kstep;
;             if (last && has_next) S.a_ready(nxt);
;             if constexpr (SP2) {
;             PG8_LDB(B0, 0, 0); PG8_LDB(B1, 0, 1); PG8_SCHED; PG8_LDA(At, 0, 0); PG8_STAGE(PG8_SA(1, 1), a1 + hstep, voffA);
;             PG8_WAIT_V(8); PG8_WAIT_L(0); PG8_BAR; PG8_MMA(0, 0, At, B0); PG8_MMA(0, 1, At, B1); PG8_BAR; PG8_SCHED;
;             PG8_LDA(At, 0, 1); PG8_STAGE(PG8_SB(0, 0), b2, voffB); PG8_STAGE(PG8_SB(0, 1), b2 + hstep, voffB); PG8_STAGE(PG8_SA(0, 0), a2, voffA);
;             PG8_WAIT_V(8); PG8_WAIT_L(0); PG8_BAR; PG8_MMA(1, 0, At, B0); PG8_MMA(1, 1, At, B1); PG8_BAR; PG8_SCHED;
;             PG8_LDB(B0, 1, 0); PG8_LDB(B1, 1, 1); PG8_SCHED; PG8_LDA(At, 1, 0); PG8_STAGE(PG8_SA(0, 1), a2 + hstep, voffA);
;             PG8_WAIT_V(8); PG8_WAIT_L(0); PG8_BAR; PG8_MMA(0, 0, At, B0); PG8_MMA(0, 1, At, B1); PG8_BAR; PG8_SCHED;
;             PG8_LDA(At, 1, 1); PG8_STAGE(PG8_SB(1, 0), b3, voffB); PG8_STAGE(PG8_SB(1, 1), b3 + hstep, voffB); PG8_STAGE(PG8_SA(1, 0), a3, voffA);
;             PG8_WAIT_V(8); PG8_WAIT_L(0); PG8_BAR; PG8_MMA(1, 0, At, B0); PG8_MMA(1, 1, At, B1); PG8_BAR; PG8_SCHED;
	s_add_i32 s57, 0, 0x18000
	s_add_i32 s58, 0, 0x1c000
	ds_read_b128 v[144:147], v240
	ds_read_b128 v[154:157], v240 offset:1024
	ds_read_b128 v[158:161], v240 offset:2048
	ds_read_b128 v[162:165], v240 offset:3072
	ds_read_b128 v[166:169], v241
	ds_read_b128 v[170:173], v241 offset:1024
	ds_read_b128 v[174:177], v241 offset:2048
	ds_read_b128 v[178:181], v241 offset:3072
	s_add_u32 s34, s34, 0x100000
	s_addc_u32 s35, s35, 0
	s_mov_b32 m0, s36
	ds_read_b128 v[182:185], v153 offset:32768
	ds_read_b128 v[186:189], v153 offset:33792
	ds_read_b128 v[194:197], v153 offset:34816
	ds_read_b128 v[198:201], v153 offset:35840
	ds_read_b128 v[202:205], v153 offset:36864
	ds_read_b128 v[206:209], v153 offset:37888
	ds_read_b128 v[210:213], v153 offset:38912
	global_load_lds_dwordx4 v128, s[34:35]
	s_mov_b32 m0, s37
	ds_read_b128 v[214:217], v153 offset:39936
	global_load_lds_dwordx4 v132, s[34:35]
	s_waitcnt vmcnt(8)
	s_waitcnt lgkmcnt(0)
	s_barrier
	s_setprio 1
	s_waitcnt lgkmcnt(0)
	v_mfma_f32_16x16x32_bf16 v[124:127], v[144:147], v[182:185], v[124:127]
	v_mfma_f32_16x16x32_bf16 v[120:123], v[158:161], v[182:185], v[120:123]
	v_mfma_f32_16x16x32_bf16 v[108:111], v[144:147], v[194:197], v[108:111]
	v_mfma_f32_16x16x32_bf16 v[104:107], v[158:161], v[194:197], v[104:107]
	v_mfma_f32_16x16x32_bf16 v[92:95], v[144:147], v[202:205], v[92:95]
	v_mfma_f32_16x16x32_bf16 v[88:91], v[158:161], v[202:205], v[88:91]
	v_mfma_f32_16x16x32_bf16 v[76:79], v[144:147], v[210:213], v[76:79]
	v_mfma_f32_16x16x32_bf16 v[72:75], v[158:161], v[210:213], v[72:75]
	v_mfma_f32_16x16x32_bf16 v[124:127], v[154:157], v[186:189], v[124:127]
	v_mfma_f32_16x16x32_bf16 v[120:123], v[162:165], v[186:189], v[120:123]
	v_mfma_f32_16x16x32_bf16 v[108:111], v[154:157], v[198:201], v[108:111]
	v_mfma_f32_16x16x32_bf16 v[104:107], v[162:165], v[198:201], v[104:107]
	v_mfma_f32_16x16x32_bf16 v[92:95], v[154:157], v[206:209], v[92:95]
	v_mfma_f32_16x16x32_bf16 v[88:91], v[162:165], v[206:209], v[88:91]
	v_mfma_f32_16x16x32_bf16 v[76:79], v[154:157], v[214:217], v[76:79]
	v_mfma_f32_16x16x32_bf16 v[72:75], v[162:165], v[214:217], v[72:75]
	s_setprio 0
	s_setprio 1
	v_mfma_f32_16x16x32_bf16 v[116:119], v[166:169], v[182:185], v[116:119]
	v_mfma_f32_16x16x32_bf16 v[112:115], v[174:177], v[182:185], v[112:115]
	v_mfma_f32_16x16x32_bf16 v[100:103], v[166:169], v[194:197], v[100:103]
	v_mfma_f32_16x16x32_bf16 v[96:99], v[174:177], v[194:197], v[96:99]
	v_mfma_f32_16x16x32_bf16 v[84:87], v[166:169], v[202:205], v[84:87]
	v_mfma_f32_16x16x32_bf16 v[80:83], v[174:177], v[202:205], v[80:83]
	v_mfma_f32_16x16x32_bf16 v[68:71], v[166:169], v[210:213], v[68:71]
	v_mfma_f32_16x16x32_bf16 v[64:67], v[174:177], v[210:213], v[64:67]
	v_mfma_f32_16x16x32_bf16 v[116:119], v[170:173], v[186:189], v[116:119]
	v_mfma_f32_16x16x32_bf16 v[112:115], v[178:181], v[186:189], v[112:115]
	v_mfma_f32_16x16x32_bf16 v[100:103], v[170:173], v[198:201], v[100:103]
	v_mfma_f32_16x16x32_bf16 v[96:99], v[178:181], v[198:201], v[96:99]
	v_mfma_f32_16x16x32_bf16 v[84:87], v[170:173], v[206:209], v[84:87]
	v_mfma_f32_16x16x32_bf16 v[80:83], v[178:181], v[206:209], v[80:83]
	v_mfma_f32_16x16x32_bf16 v[68:71], v[170:173], v[214:217], v[68:71]
	v_mfma_f32_16x16x32_bf16 v[64:67], v[178:181], v[214:217], v[64:67]
	s_setprio 0
	s_barrier
	s_add_i32 s34, s57, s0
	s_mov_b32 m0, s34
	ds_read_b128 v[182:185], v153 offset:49152
	ds_read_b128 v[186:189], v153 offset:50176
	ds_read_b128 v[194:197], v153 offset:51200
	ds_read_b128 v[198:201], v153 offset:52224
	global_load_lds_dwordx4 v130, vcc
	s_add_i32 m0, s34, 0x2000
	s_add_u32 s28, s28, 0x100080
	s_addc_u32 s29, s29, 0
	s_add_i32 s34, s58, s0
	global_load_lds_dwordx4 v134, vcc
	s_mov_b32 m0, s34
	ds_read_b128 v[214:217], v153 offset:56320
	global_load_lds_dwordx4 v130, s[28:29]
	s_add_i32 m0, s34, 0x2000
	ds_read_b128 v[210:213], v153 offset:55296
	global_load_lds_dwordx4 v134, s[28:29]
	s_mov_b32 m0, s39
	ds_read_b128 v[206:209], v153 offset:54272
	global_load_lds_dwordx4 v128, s[100:101]
	s_mov_b32 m0, s40
	ds_read_b128 v[202:205], v153 offset:53248
	global_load_lds_dwordx4 v132, s[100:101]
	s_waitcnt vmcnt(8)
	s_waitcnt lgkmcnt(0)
	s_barrier
	s_setprio 1
	s_waitcnt lgkmcnt(0)
	v_mfma_f32_16x16x32_bf16 v[60:63], v[144:147], v[182:185], v[60:63]
	v_mfma_f32_16x16x32_bf16 v[56:59], v[158:161], v[182:185], v[56:59]
	v_mfma_f32_16x16x32_bf16 v[44:47], v[144:147], v[194:197], v[44:47]
	v_mfma_f32_16x16x32_bf16 v[40:43], v[158:161], v[194:197], v[40:43]
	v_mfma_f32_16x16x32_bf16 v[28:31], v[144:147], v[202:205], v[28:31]
	v_mfma_f32_16x16x32_bf16 v[24:27], v[158:161], v[202:205], v[24:27]
	v_mfma_f32_16x16x32_bf16 v[12:15], v[144:147], v[210:213], v[12:15]
	v_mfma_f32_16x16x32_bf16 v[8:11], v[158:161], v[210:213], v[8:11]
	v_mfma_f32_16x16x32_bf16 v[60:63], v[154:157], v[186:189], v[60:63]
	v_mfma_f32_16x16x32_bf16 v[56:59], v[162:165], v[186:189], v[56:59]
	v_mfma_f32_16x16x32_bf16 v[44:47], v[154:157], v[198:201], v[44:47]
	v_mfma_f32_16x16x32_bf16 v[40:43], v[162:165], v[198:201], v[40:43]
	v_mfma_f32_16x16x32_bf16 v[28:31], v[154:157], v[206:209], v[28:31]
	v_mfma_f32_16x16x32_bf16 v[24:27], v[162:165], v[206:209], v[24:27]
	v_mfma_f32_16x16x32_bf16 v[12:15], v[154:157], v[214:217], v[12:15]
	v_mfma_f32_16x16x32_bf16 v[8:11], v[162:165], v[214:217], v[8:11]
	s_setprio 0
	s_setprio 1
	v_mfma_f32_16x16x32_bf16 v[52:55], v[166:169], v[182:185], v[52:55]
	v_mfma_f32_16x16x32_bf16 v[48:51], v[174:177], v[182:185], v[48:51]
	v_mfma_f32_16x16x32_bf16 v[36:39], v[166:169], v[194:197], v[36:39]
	v_mfma_f32_16x16x32_bf16 v[32:35], v[174:177], v[194:197], v[32:35]
	v_mfma_f32_16x16x32_bf16 v[20:23], v[166:169], v[202:205], v[20:23]
	v_mfma_f32_16x16x32_bf16 v[16:19], v[174:177], v[202:205], v[16:19]
	v_mfma_f32_16x16x32_bf16 v[4:7], v[166:169], v[210:213], v[4:7]
	v_mfma_f32_16x16x32_bf16 v[0:3], v[174:177], v[210:213], v[0:3]
	v_mfma_f32_16x16x32_bf16 v[52:55], v[170:173], v[186:189], v[52:55]
	v_mfma_f32_16x16x32_bf16 v[48:51], v[178:181], v[186:189], v[48:51]
	v_mfma_f32_16x16x32_bf16 v[36:39], v[170:173], v[198:201], v[36:39]
	v_mfma_f32_16x16x32_bf16 v[32:35], v[178:181], v[198:201], v[32:35]
	v_mfma_f32_16x16x32_bf16 v[20:23], v[170:173], v[206:209], v[20:23]
	v_mfma_f32_16x16x32_bf16 v[16:19], v[178:181], v[206:209], v[16:19]
	v_mfma_f32_16x16x32_bf16 v[4:7], v[170:173], v[214:217], v[4:7]
	v_mfma_f32_16x16x32_bf16 v[0:3], v[178:181], v[214:217], v[0:3]
	s_setprio 0
	s_barrier
	s_add_i32 s56, s56, 2
	s_add_u32 s26, s26, 0x100
	s_addc_u32 s27, s27, 0
	s_add_u32 s50, s50, 0x100
	s_addc_u32 s51, s51, 0
	s_cmp_gt_u32 s56, 61
	s_cbranch_scc0 .LBB0_501
	s_and_b64 vcc, exec, s[14:15]
	s_cbranch_vccz .LBB0_504
	s_barrier
